# GEMM compute blocks: duplicate post-barrier lgkmcnt(0) removed (16); scan step: 2 obsolete s_nop 2 removed
# baseline (speedup 1.0000x reference)
; #define PG8_STAGE(bufoff, gbase, voff) do { _Pragma("unroll") for (int _i = 0; _i < 2; ++_i) \
;         __builtin_amdgcn_global_load_lds((const unsigned*)((const char*)(gbase) + (voff)[_i]), (LAS unsigned*)(lds + (bufoff) + ldsw + _i * 8192), 16, 0, 0); } while (0)
; #define PG8_LDA(dst, b, h) do { _Pragma("unroll") for (int m = 0; m < 4; ++m) _Pragma("unroll") for (int k = 0; k < 2; ++k) dst[m][k] = *(const LAS bf16x8*)(lds + PG8_SA(b, h) + aoff + m * 2048 + k * 1024); } while (0)
; #define PG8_LDB(dst, b, h) do { _Pragma("unroll") for (int n = 0; n < 2; ++n) _Pragma("unroll") for (int k = 0; k < 2; ++k) dst[n][k] = *(const LAS bf16x8*)(lds + PG8_SB(b, h) + boff + n * 2048 + k * 1024); } while (0)
; #define PG8_MMA(ai, bj, At, Bt) do { __builtin_amdgcn_s_setprio(1); _Pragma("unroll") for (int m = 0; m < 4; ++m) _Pragma("unroll") for (int n = 0; n < 2; ++n) _Pragma("unroll") for (int k = 0; k < 2; ++k) \
;         acc[ai][bj][m][n] = __builtin_amdgcn_mfma_f32_16x16x32_bf16(Bt[n][k], At[m][k], acc[ai][bj][m][n], 0, 0, 0); __builtin_amdgcn_s_setprio(0); } while (0)
; #define PG8_WAIT_V(n) asm volatile("s_waitcnt vmcnt(" #n ")" ::: "memory")
; #define PG8_WAIT_L(n) asm volatile("s_waitcnt lgkmcnt(" #n ")" ::: "memory")
; #define PG8_BAR __builtin_amdgcn_s_barrier()
; #define PG8_SCHED __builtin_amdgcn_sched_barrier(0)
; template <class Epi>
; DI void gemm_phase(int wid0, LAS unsigned char* lds, const Gemm g, const StaticOrder& S, const Epi& E) {
;     ...
;             PG8_LDB(B0, 0, 0); PG8_LDB(B1, 0, 1); PG8_SCHED; PG8_LDA(At, 0, 0); PG8_STAGE(PG8_SA(1, 1), a1 + hstep, voffA);
;             PG8_WAIT_V(8); PG8_WAIT_L(0); PG8_BAR; PG8_MMA(0, 0, At, B0); PG8_MMA(0, 1, At, B1); PG8_BAR; PG8_SCHED;
;             PG8_LDA(At, 0, 1); PG8_STAGE(PG8_SB(0, 0), b2, voffB); PG8_STAGE(PG8_SB(0, 1), b2 + hstep, voffB); PG8_STAGE(PG8_SA(0, 0), a2, voffA);
.LBB0_58:
	s_add_u32 s68, s22, 0xfffc0080
	s_addc_u32 s69, s23, -1
	s_add_i32 s80, 0, 0x10000
	s_cmp_eq_u32 s79, 12
	s_cselect_b32 s71, s15, s69
	s_cselect_b32 s70, s40, s68
	v_add_u32_e32 v144, s80, v147
	s_cselect_b32 s69, s13, s67
	s_cselect_b32 s68, s41, s66
	s_add_i32 s82, 0, 0x14000
	ds_read_b128 v[140:143], v144
	ds_read_b128 v[150:153], v144 offset:1024
	ds_read_b128 v[154:157], v144 offset:2048
	ds_read_b128 v[158:161], v144 offset:3072
	v_add_u32_e32 v144, s82, v147
	ds_read_b128 v[176:179], v144
	ds_read_b128 v[180:183], v144 offset:1024
	ds_read_b128 v[190:193], v144 offset:2048
	ds_read_b128 v[194:197], v144 offset:3072
	s_add_i32 m0, s73, 0xc000
	ds_read_b128 v[198:201], v149
	ds_read_b128 v[202:205], v149 offset:1024
	ds_read_b128 v[206:209], v149 offset:2048
	ds_read_b128 v[210:213], v149 offset:3072
	ds_read_b128 v[214:217], v149 offset:4096
	ds_read_b128 v[218:221], v149 offset:5120
	ds_read_b128 v[222:225], v149 offset:6144
	ds_read_b128 v[226:229], v149 offset:7168
	global_load_lds_dwordx4 v136, s[22:23]
	s_add_i32 m0, s73, 0xe000
	s_nop 0
	global_load_lds_dwordx4 v138, s[22:23]
	s_waitcnt vmcnt(8)
	s_waitcnt lgkmcnt(0)
	s_barrier
	s_setprio 1
	v_mfma_f32_16x16x32_bf16 v[126:129], v[140:143], v[198:201], v[126:129]
	v_mfma_f32_16x16x32_bf16 v[122:125], v[154:157], v[198:201], v[122:125]
	v_mfma_f32_16x16x32_bf16 v[110:113], v[140:143], v[206:209], v[110:113]
	v_mfma_f32_16x16x32_bf16 v[106:109], v[154:157], v[206:209], v[106:109]
	v_mfma_f32_16x16x32_bf16 v[94:97], v[140:143], v[214:217], v[94:97]
	v_mfma_f32_16x16x32_bf16 v[90:93], v[154:157], v[214:217], v[90:93]
	v_mfma_f32_16x16x32_bf16 v[78:81], v[140:143], v[222:225], v[78:81]
	v_mfma_f32_16x16x32_bf16 v[74:77], v[154:157], v[222:225], v[74:77]
	v_mfma_f32_16x16x32_bf16 v[126:129], v[150:153], v[202:205], v[126:129]
	v_mfma_f32_16x16x32_bf16 v[122:125], v[158:161], v[202:205], v[122:125]
	v_mfma_f32_16x16x32_bf16 v[110:113], v[150:153], v[210:213], v[110:113]
	v_mfma_f32_16x16x32_bf16 v[106:109], v[158:161], v[210:213], v[106:109]
	v_mfma_f32_16x16x32_bf16 v[94:97], v[150:153], v[218:221], v[94:97]
	v_mfma_f32_16x16x32_bf16 v[90:93], v[158:161], v[218:221], v[90:93]
	v_mfma_f32_16x16x32_bf16 v[78:81], v[150:153], v[226:229], v[78:81]
	v_mfma_f32_16x16x32_bf16 v[74:77], v[158:161], v[226:229], v[74:77]
	v_mfma_f32_16x16x32_bf16 v[118:121], v[176:179], v[198:201], v[118:121]
	v_mfma_f32_16x16x32_bf16 v[114:117], v[190:193], v[198:201], v[114:117]
	v_mfma_f32_16x16x32_bf16 v[102:105], v[176:179], v[206:209], v[102:105]
	v_mfma_f32_16x16x32_bf16 v[98:101], v[190:193], v[206:209], v[98:101]
	v_mfma_f32_16x16x32_bf16 v[86:89], v[176:179], v[214:217], v[86:89]
	v_mfma_f32_16x16x32_bf16 v[82:85], v[190:193], v[214:217], v[82:85]
	v_mfma_f32_16x16x32_bf16 v[70:73], v[176:179], v[222:225], v[70:73]
	v_mfma_f32_16x16x32_bf16 v[66:69], v[190:193], v[222:225], v[66:69]
	v_mfma_f32_16x16x32_bf16 v[118:121], v[180:183], v[202:205], v[118:121]
	v_mfma_f32_16x16x32_bf16 v[114:117], v[194:197], v[202:205], v[114:117]
	v_mfma_f32_16x16x32_bf16 v[102:105], v[180:183], v[210:213], v[102:105]
	v_mfma_f32_16x16x32_bf16 v[98:101], v[194:197], v[210:213], v[98:101]
	v_mfma_f32_16x16x32_bf16 v[86:89], v[180:183], v[218:221], v[86:89]
	v_mfma_f32_16x16x32_bf16 v[82:85], v[194:197], v[218:221], v[82:85]
	v_mfma_f32_16x16x32_bf16 v[70:73], v[180:183], v[226:229], v[70:73]
	v_mfma_f32_16x16x32_bf16 v[66:69], v[194:197], v[226:229], v[66:69]
	s_setprio 0
	s_barrier
	s_add_i32 s80, s80, s72
	v_lshl_add_u64 v[144:145], s[68:69], 0, v[0:1]
	s_mov_b32 m0, s80
	ds_read_b128 v[198:201], v149 offset:16384
	ds_read_b128 v[202:205], v149 offset:17408
	ds_read_b128 v[206:209], v149 offset:18432
	ds_read_b128 v[210:213], v149 offset:19456
	ds_read_b128 v[214:217], v149 offset:20480
	ds_read_b128 v[218:221], v149 offset:21504
	ds_read_b128 v[222:225], v149 offset:22528
	ds_read_b128 v[226:229], v149 offset:23552
	global_load_lds_dwordx4 v[144:145], off
	s_add_i32 m0, s80, 0x2000
	s_add_u32 s80, s68, 0x40000
	v_lshl_add_u64 v[162:163], s[68:69], 0, v[130:131]
	s_addc_u32 s81, s69, 0
	s_add_i32 s82, s82, s72
	global_load_lds_dwordx4 v[162:163], off
	s_mov_b32 m0, s82
	v_lshl_add_u64 v[236:237], s[70:71], 0, v[132:133]
	global_load_lds_dwordx4 v0, s[80:81]
	s_add_i32 m0, s82, 0x2000
	s_nop 0
	global_load_lds_dwordx4 v130, s[80:81]
	v_lshl_add_u64 v[230:231], s[70:71], 0, v[134:135]
	s_mov_b32 m0, s73
	s_nop 0
	global_load_lds_dwordx4 v[230:231], off
	s_mov_b32 m0, s74
	s_nop 0
	global_load_lds_dwordx4 v[236:237], off
	s_waitcnt vmcnt(8)
	s_waitcnt lgkmcnt(0)
	s_barrier
; #define PG8_STAGE(bufoff, gbase, voff) do { _Pragma("unroll") for (int _i = 0; _i < 2; ++_i) \
;         __builtin_amdgcn_global_load_lds((const unsigned*)((const char*)(gbase) + (voff)[_i]), (LAS unsigned*)(lds + (bufoff) + ldsw + _i * 8192), 16, 0, 0); } while (0)
; #define PG8_LDA(dst, b, h) do { _Pragma("unroll") for (int m = 0; m < 4; ++m) _Pragma("unroll") for (int k = 0; k < 2; ++k) dst[m][k] = *(const LAS bf16x8*)(lds + PG8_SA(b, h) + aoff + m * 2048 + k * 1024); } while (0)
; #define PG8_LDB(dst, b, h) do { _Pragma("unroll") for (int n = 0; n < 2; ++n) _Pragma("unroll") for (int k = 0; k < 2; ++k) dst[n][k] = *(const LAS bf16x8*)(lds + PG8_SB(b, h) + boff + n * 2048 + k * 1024); } while (0)
; #define PG8_MMA(ai, bj, At, Bt) do { __builtin_amdgcn_s_setprio(1); _Pragma("unroll") for (int m = 0; m < 4; ++m) _Pragma("unroll") for (int n = 0; n < 2; ++n) _Pragma("unroll") for (int k = 0; k < 2; ++k) \
;         acc[ai][bj][m][n] = __builtin_amdgcn_mfma_f32_16x16x32_bf16(Bt[n][k], At[m][k], acc[ai][bj][m][n], 0, 0, 0); __builtin_amdgcn_s_setprio(0); } while (0)
; #define PG8_WAIT_V(n) asm volatile("s_waitcnt vmcnt(" #n ")" ::: "memory")
; #define PG8_WAIT_L(n) asm volatile("s_waitcnt lgkmcnt(" #n ")" ::: "memory")
; #define PG8_BAR __builtin_amdgcn_s_barrier()
; #define PG8_SCHED __builtin_amdgcn_sched_barrier(0)
; template <class Epi>
; DI void gemm_phase(int wid0, LAS unsigned char* lds, const Gemm g, const StaticOrder& S, const Epi& E) {
;     ...
;             PG8_WAIT_V(8); PG8_WAIT_L(0); PG8_BAR; PG8_MMA(1, 0, At, B0); PG8_MMA(1, 1, At, B1); PG8_BAR; PG8_SCHED;
;             PG8_LDB(B0, 1, 0); PG8_LDB(B1, 1, 1); PG8_SCHED; PG8_LDA(At, 1, 0); PG8_STAGE(PG8_SA(0, 1), a2 + hstep, voffA);
;             PG8_WAIT_V(8); PG8_WAIT_L(0); PG8_BAR; PG8_MMA(0, 0, At, B0); PG8_MMA(0, 1, At, B1); PG8_BAR; PG8_SCHED;
	s_setprio 1
	v_mfma_f32_16x16x32_bf16 v[62:65], v[140:143], v[198:201], v[62:65]
	v_mfma_f32_16x16x32_bf16 v[58:61], v[154:157], v[198:201], v[58:61]
	v_mfma_f32_16x16x32_bf16 v[46:49], v[140:143], v[206:209], v[46:49]
	v_mfma_f32_16x16x32_bf16 v[42:45], v[154:157], v[206:209], v[42:45]
	v_mfma_f32_16x16x32_bf16 v[30:33], v[140:143], v[214:217], v[30:33]
	v_mfma_f32_16x16x32_bf16 v[26:29], v[154:157], v[214:217], v[26:29]
	v_mfma_f32_16x16x32_bf16 v[14:17], v[140:143], v[222:225], v[14:17]
	v_mfma_f32_16x16x32_bf16 v[10:13], v[154:157], v[222:225], v[10:13]
	v_mfma_f32_16x16x32_bf16 v[62:65], v[150:153], v[202:205], v[62:65]
	v_mfma_f32_16x16x32_bf16 v[58:61], v[158:161], v[202:205], v[58:61]
	v_mfma_f32_16x16x32_bf16 v[46:49], v[150:153], v[210:213], v[46:49]
	v_mfma_f32_16x16x32_bf16 v[42:45], v[158:161], v[210:213], v[42:45]
	v_mfma_f32_16x16x32_bf16 v[30:33], v[150:153], v[218:221], v[30:33]
	v_mfma_f32_16x16x32_bf16 v[26:29], v[158:161], v[218:221], v[26:29]
	v_mfma_f32_16x16x32_bf16 v[14:17], v[150:153], v[226:229], v[14:17]
	v_mfma_f32_16x16x32_bf16 v[10:13], v[158:161], v[226:229], v[10:13]
	v_mfma_f32_16x16x32_bf16 v[54:57], v[176:179], v[198:201], v[54:57]
	v_mfma_f32_16x16x32_bf16 v[50:53], v[190:193], v[198:201], v[50:53]
	v_mfma_f32_16x16x32_bf16 v[38:41], v[176:179], v[206:209], v[38:41]
	v_mfma_f32_16x16x32_bf16 v[34:37], v[190:193], v[206:209], v[34:37]
	v_mfma_f32_16x16x32_bf16 v[22:25], v[176:179], v[214:217], v[22:25]
	v_mfma_f32_16x16x32_bf16 v[18:21], v[190:193], v[214:217], v[18:21]
	v_mfma_f32_16x16x32_bf16 v[6:9], v[176:179], v[222:225], v[6:9]
	v_mfma_f32_16x16x32_bf16 v[2:5], v[190:193], v[222:225], v[2:5]
	v_mfma_f32_16x16x32_bf16 v[54:57], v[180:183], v[202:205], v[54:57]
	v_mfma_f32_16x16x32_bf16 v[50:53], v[194:197], v[202:205], v[50:53]
	v_mfma_f32_16x16x32_bf16 v[38:41], v[180:183], v[210:213], v[38:41]
	v_mfma_f32_16x16x32_bf16 v[34:37], v[194:197], v[210:213], v[34:37]
	v_mfma_f32_16x16x32_bf16 v[22:25], v[180:183], v[218:221], v[22:25]
	v_mfma_f32_16x16x32_bf16 v[18:21], v[194:197], v[218:221], v[18:21]
	v_mfma_f32_16x16x32_bf16 v[6:9], v[180:183], v[226:229], v[6:9]
	v_mfma_f32_16x16x32_bf16 v[2:5], v[194:197], v[226:229], v[2:5]
	s_setprio 0
	s_barrier
	s_add_i32 s80, 0, 0x18000
	s_add_i32 s81, 0, 0x1c000
	v_add_u32_e32 v158, s80, v147
	v_add_u32_e32 v189, s81, v147
	ds_read_b128 v[140:143], v158
	ds_read_b128 v[150:153], v158 offset:1024
	ds_read_b128 v[154:157], v158 offset:2048
	ds_read_b128 v[158:161], v158 offset:3072
	ds_read_b128 v[176:179], v189
	ds_read_b128 v[180:183], v189 offset:1024
	ds_read_b128 v[190:193], v189 offset:2048
	ds_read_b128 v[194:197], v189 offset:3072
	s_add_u32 s70, s70, 0x40000
	s_addc_u32 s71, s71, 0
	s_mov_b32 m0, s75
	ds_read_b128 v[198:201], v149 offset:32768
	ds_read_b128 v[202:205], v149 offset:33792
	ds_read_b128 v[206:209], v149 offset:34816
	ds_read_b128 v[210:213], v149 offset:35840
	ds_read_b128 v[214:217], v149 offset:36864
	ds_read_b128 v[218:221], v149 offset:37888
	ds_read_b128 v[222:225], v149 offset:38912
	ds_read_b128 v[226:229], v149 offset:39936
	global_load_lds_dwordx4 v134, s[70:71]
	v_lshl_add_u64 v[238:239], s[70:71], 0, v[132:133]
	s_mov_b32 m0, s76
	s_nop 0
	global_load_lds_dwordx4 v[238:239], off
	s_waitcnt vmcnt(8)
	s_waitcnt lgkmcnt(0)
	s_barrier
	s_setprio 1
	v_mfma_f32_16x16x32_bf16 v[126:129], v[140:143], v[198:201], v[126:129]
	v_mfma_f32_16x16x32_bf16 v[122:125], v[154:157], v[198:201], v[122:125]
	v_mfma_f32_16x16x32_bf16 v[110:113], v[140:143], v[206:209], v[110:113]
	v_mfma_f32_16x16x32_bf16 v[106:109], v[154:157], v[206:209], v[106:109]
	v_mfma_f32_16x16x32_bf16 v[94:97], v[140:143], v[214:217], v[94:97]
	v_mfma_f32_16x16x32_bf16 v[90:93], v[154:157], v[214:217], v[90:93]
	v_mfma_f32_16x16x32_bf16 v[78:81], v[140:143], v[222:225], v[78:81]
	v_mfma_f32_16x16x32_bf16 v[74:77], v[154:157], v[222:225], v[74:77]
	v_mfma_f32_16x16x32_bf16 v[126:129], v[150:153], v[202:205], v[126:129]
	v_mfma_f32_16x16x32_bf16 v[122:125], v[158:161], v[202:205], v[122:125]
	v_mfma_f32_16x16x32_bf16 v[110:113], v[150:153], v[210:213], v[110:113]
	v_mfma_f32_16x16x32_bf16 v[106:109], v[158:161], v[210:213], v[106:109]
	v_mfma_f32_16x16x32_bf16 v[94:97], v[150:153], v[218:221], v[94:97]
	v_mfma_f32_16x16x32_bf16 v[90:93], v[158:161], v[218:221], v[90:93]
	v_mfma_f32_16x16x32_bf16 v[78:81], v[150:153], v[226:229], v[78:81]
	v_mfma_f32_16x16x32_bf16 v[74:77], v[158:161], v[226:229], v[74:77]
	v_mfma_f32_16x16x32_bf16 v[118:121], v[176:179], v[198:201], v[118:121]
	v_mfma_f32_16x16x32_bf16 v[114:117], v[190:193], v[198:201], v[114:117]
	v_mfma_f32_16x16x32_bf16 v[102:105], v[176:179], v[206:209], v[102:105]
	v_mfma_f32_16x16x32_bf16 v[98:101], v[190:193], v[206:209], v[98:101]
	v_mfma_f32_16x16x32_bf16 v[86:89], v[176:179], v[214:217], v[86:89]
	v_mfma_f32_16x16x32_bf16 v[82:85], v[190:193], v[214:217], v[82:85]
	v_mfma_f32_16x16x32_bf16 v[70:73], v[176:179], v[222:225], v[70:73]
	v_mfma_f32_16x16x32_bf16 v[66:69], v[190:193], v[222:225], v[66:69]
	v_mfma_f32_16x16x32_bf16 v[118:121], v[180:183], v[202:205], v[118:121]
	v_mfma_f32_16x16x32_bf16 v[114:117], v[194:197], v[202:205], v[114:117]
	v_mfma_f32_16x16x32_bf16 v[102:105], v[180:183], v[210:213], v[102:105]
	v_mfma_f32_16x16x32_bf16 v[98:101], v[194:197], v[210:213], v[98:101]
	v_mfma_f32_16x16x32_bf16 v[86:89], v[180:183], v[218:221], v[86:89]
	v_mfma_f32_16x16x32_bf16 v[82:85], v[194:197], v[218:221], v[82:85]
	v_mfma_f32_16x16x32_bf16 v[70:73], v[180:183], v[226:229], v[70:73]
	v_mfma_f32_16x16x32_bf16 v[66:69], v[194:197], v[226:229], v[66:69]
	s_setprio 0
	s_barrier
; #define PG8_STAGE(bufoff, gbase, voff) do { _Pragma("unroll") for (int _i = 0; _i < 2; ++_i) \
;         __builtin_amdgcn_global_load_lds((const unsigned*)((const char*)(gbase) + (voff)[_i]), (LAS unsigned*)(lds + (bufoff) + ldsw + _i * 8192), 16, 0, 0); } while (0)
; #define PG8_LDA(dst, b, h) do { _Pragma("unroll") for (int m = 0; m < 4; ++m) _Pragma("unroll") for (int k = 0; k < 2; ++k) dst[m][k] = *(const LAS bf16x8*)(lds + PG8_SA(b, h) + aoff + m * 2048 + k * 1024); } while (0)
; #define PG8_MMA(ai, bj, At, Bt) do { __builtin_amdgcn_s_setprio(1); _Pragma("unroll") for (int m = 0; m < 4; ++m) _Pragma("unroll") for (int n = 0; n < 2; ++n) _Pragma("unroll") for (int k = 0; k < 2; ++k) \
;         acc[ai][bj][m][n] = __builtin_amdgcn_mfma_f32_16x16x32_bf16(Bt[n][k], At[m][k], acc[ai][bj][m][n], 0, 0, 0); __builtin_amdgcn_s_setprio(0); } while (0)
; #define PG8_WAIT_V(n) asm volatile("s_waitcnt vmcnt(" #n ")" ::: "memory")
; #define PG8_WAIT_L(n) asm volatile("s_waitcnt lgkmcnt(" #n ")" ::: "memory")
; #define PG8_BAR __builtin_amdgcn_s_barrier()
; #define PG8_SCHED __builtin_amdgcn_sched_barrier(0)
; template <class Epi>
; DI void gemm_phase(int wid0, LAS unsigned char* lds, const Gemm g, const StaticOrder& S, const Epi& E) {
;     ...
;             PG8_LDA(At, 1, 1); PG8_STAGE(PG8_SB(1, 0), b3, voffB); PG8_STAGE(PG8_SB(1, 1), b3 + hstep, voffB); PG8_STAGE(PG8_SA(1, 0), a3, voffA);
;             PG8_WAIT_V(8); PG8_WAIT_L(0); PG8_BAR; PG8_MMA(1, 0, At, B0); PG8_MMA(1, 1, At, B1); PG8_BAR; PG8_SCHED;
;         }
	s_add_i32 s70, s80, s72
	v_lshl_add_u64 v[144:145], v[144:145], 0, s[30:31]
	s_mov_b32 m0, s70
	ds_read_b128 v[198:201], v149 offset:49152
	ds_read_b128 v[202:205], v149 offset:50176
	ds_read_b128 v[206:209], v149 offset:51200
	ds_read_b128 v[210:213], v149 offset:52224
	ds_read_b128 v[214:217], v149 offset:53248
	ds_read_b128 v[218:221], v149 offset:54272
	ds_read_b128 v[222:225], v149 offset:55296
	ds_read_b128 v[226:229], v149 offset:56320
	global_load_lds_dwordx4 v[144:145], off
	s_add_i32 m0, s70, 0x2000
	s_add_u32 s68, s68, 0x40080
	v_lshl_add_u64 v[144:145], v[162:163], 0, s[30:31]
	s_addc_u32 s69, s69, 0
	s_add_i32 s70, s81, s72
	global_load_lds_dwordx4 v[144:145], off
	s_mov_b32 m0, s70
	s_nop 0
	global_load_lds_dwordx4 v0, s[68:69]
	s_add_i32 m0, s70, 0x2000
	s_nop 0
	global_load_lds_dwordx4 v130, s[68:69]
	v_lshl_add_u64 v[144:145], v[230:231], 0, s[30:31]
	s_mov_b32 m0, s2
	s_nop 0
	global_load_lds_dwordx4 v[144:145], off
	v_lshl_add_u64 v[144:145], v[236:237], 0, s[30:31]
	s_mov_b32 m0, s77
	s_nop 0
	global_load_lds_dwordx4 v[144:145], off
	s_waitcnt vmcnt(8)
	s_waitcnt lgkmcnt(0)
	s_barrier
	s_setprio 1
	v_mfma_f32_16x16x32_bf16 v[62:65], v[140:143], v[198:201], v[62:65]
	v_mfma_f32_16x16x32_bf16 v[58:61], v[154:157], v[198:201], v[58:61]
	v_mfma_f32_16x16x32_bf16 v[46:49], v[140:143], v[206:209], v[46:49]
	v_mfma_f32_16x16x32_bf16 v[42:45], v[154:157], v[206:209], v[42:45]
	v_mfma_f32_16x16x32_bf16 v[30:33], v[140:143], v[214:217], v[30:33]
	v_mfma_f32_16x16x32_bf16 v[26:29], v[154:157], v[214:217], v[26:29]
	v_mfma_f32_16x16x32_bf16 v[14:17], v[140:143], v[222:225], v[14:17]
	v_mfma_f32_16x16x32_bf16 v[10:13], v[154:157], v[222:225], v[10:13]
	v_mfma_f32_16x16x32_bf16 v[62:65], v[150:153], v[202:205], v[62:65]
	v_mfma_f32_16x16x32_bf16 v[58:61], v[158:161], v[202:205], v[58:61]
	v_mfma_f32_16x16x32_bf16 v[46:49], v[150:153], v[210:213], v[46:49]
	v_mfma_f32_16x16x32_bf16 v[42:45], v[158:161], v[210:213], v[42:45]
	v_mfma_f32_16x16x32_bf16 v[30:33], v[150:153], v[218:221], v[30:33]
	v_mfma_f32_16x16x32_bf16 v[26:29], v[158:161], v[218:221], v[26:29]
	v_mfma_f32_16x16x32_bf16 v[14:17], v[150:153], v[226:229], v[14:17]
	v_mfma_f32_16x16x32_bf16 v[10:13], v[158:161], v[226:229], v[10:13]
	v_mfma_f32_16x16x32_bf16 v[54:57], v[176:179], v[198:201], v[54:57]
	v_mfma_f32_16x16x32_bf16 v[50:53], v[190:193], v[198:201], v[50:53]
	v_mfma_f32_16x16x32_bf16 v[38:41], v[176:179], v[206:209], v[38:41]
	v_mfma_f32_16x16x32_bf16 v[34:37], v[190:193], v[206:209], v[34:37]
	v_mfma_f32_16x16x32_bf16 v[22:25], v[176:179], v[214:217], v[22:25]
	v_mfma_f32_16x16x32_bf16 v[18:21], v[190:193], v[214:217], v[18:21]
	v_mfma_f32_16x16x32_bf16 v[6:9], v[176:179], v[222:225], v[6:9]
	v_mfma_f32_16x16x32_bf16 v[2:5], v[190:193], v[222:225], v[2:5]
	v_mfma_f32_16x16x32_bf16 v[54:57], v[180:183], v[202:205], v[54:57]
	v_mfma_f32_16x16x32_bf16 v[50:53], v[194:197], v[202:205], v[50:53]
	v_mfma_f32_16x16x32_bf16 v[38:41], v[180:183], v[210:213], v[38:41]
	v_mfma_f32_16x16x32_bf16 v[34:37], v[194:197], v[210:213], v[34:37]
	v_mfma_f32_16x16x32_bf16 v[22:25], v[180:183], v[218:221], v[22:25]
	v_mfma_f32_16x16x32_bf16 v[18:21], v[194:197], v[218:221], v[18:21]
	v_mfma_f32_16x16x32_bf16 v[6:9], v[180:183], v[226:229], v[6:9]
	v_mfma_f32_16x16x32_bf16 v[2:5], v[194:197], v[226:229], v[2:5]
	s_setprio 0
	s_barrier
	s_add_i32 s79, s79, 2
	s_add_u32 s22, s22, 0x100
	s_addc_u32 s23, s23, 0
	s_add_u32 s66, s66, 0x100
	s_addc_u32 s67, s67, 0
	s_cmp_gt_u32 s79, 13
	s_cbranch_scc0 .LBB0_58
	s_and_b64 vcc, exec, s[10:11]
	s_movk_i32 s79, 0x3fff
	s_movk_i32 s40, 0x7fff
	v_readlane_b32 s41, v245, 48
	s_cbranch_vccz .LBB0_61
	s_barrier

; #define PG8_STAGE(bufoff, gbase, voff) do { _Pragma("unroll") for (int _i = 0; _i < 2; ++_i) \
;         __builtin_amdgcn_global_load_lds((const unsigned*)((const char*)(gbase) + (voff)[_i]), (LAS unsigned*)(lds + (bufoff) + ldsw + _i * 8192), 16, 0, 0); } while (0)
; #define PG8_LDA(dst, b, h) do { _Pragma("unroll") for (int m = 0; m < 4; ++m) _Pragma("unroll") for (int k = 0; k < 2; ++k) dst[m][k] = *(const LAS bf16x8*)(lds + PG8_SA(b, h) + aoff + m * 2048 + k * 1024); } while (0)
; #define PG8_LDB(dst, b, h) do { _Pragma("unroll") for (int n = 0; n < 2; ++n) _Pragma("unroll") for (int k = 0; k < 2; ++k) dst[n][k] = *(const LAS bf16x8*)(lds + PG8_SB(b, h) + boff + n * 2048 + k * 1024); } while (0)
; #define PG8_MMA(ai, bj, At, Bt) do { __builtin_amdgcn_s_setprio(1); _Pragma("unroll") for (int m = 0; m < 4; ++m) _Pragma("unroll") for (int n = 0; n < 2; ++n) _Pragma("unroll") for (int k = 0; k < 2; ++k) \
;         acc[ai][bj][m][n] = __builtin_amdgcn_mfma_f32_16x16x32_bf16(Bt[n][k], At[m][k], acc[ai][bj][m][n], 0, 0, 0); __builtin_amdgcn_s_setprio(0); } while (0)
; #define PG8_WAIT_V(n) asm volatile("s_waitcnt vmcnt(" #n ")" ::: "memory")
; #define PG8_WAIT_L(n) asm volatile("s_waitcnt lgkmcnt(" #n ")" ::: "memory")
; #define PG8_BAR __builtin_amdgcn_s_barrier()
; #define PG8_SCHED __builtin_amdgcn_sched_barrier(0)
; template <class Epi>
; DI void gemm_phase(int wid0, LAS unsigned char* lds, const Gemm g, const StaticOrder& S, const Epi& E) {
;     ...
;             PG8_LDB(B0, 0, 0); PG8_LDB(B1, 0, 1); PG8_SCHED; PG8_LDA(At, 0, 0); PG8_STAGE(PG8_SA(1, 1), a1 + hstep, voffA);
;             PG8_WAIT_V(8); PG8_WAIT_L(0); PG8_BAR; PG8_MMA(0, 0, At, B0); PG8_MMA(0, 1, At, B1); PG8_BAR; PG8_SCHED;
;             PG8_LDA(At, 0, 1); PG8_STAGE(PG8_SB(0, 0), b2, voffB); PG8_STAGE(PG8_SB(0, 1), b2 + hstep, voffB); PG8_STAGE(PG8_SA(0, 0), a2, voffA);
.LBB0_139:
	s_add_u32 s22, s20, 0xfffc0080
	s_addc_u32 s23, s21, -1
	s_add_i32 s72, 0, 0x10000
	s_cmp_eq_u32 s71, 12
	s_cselect_b32 s39, s15, s23
	s_cselect_b32 s38, s66, s22
	v_add_u32_e32 v0, s72, v143
	s_cselect_b32 s23, s13, s70
	s_cselect_b32 s22, s67, s69
	s_add_i32 s74, 0, 0x14000
	ds_read_b128 v[146:149], v0
	ds_read_b128 v[150:153], v0 offset:1024
	ds_read_b128 v[154:157], v0 offset:2048
	ds_read_b128 v[158:161], v0 offset:3072
	v_add_u32_e32 v0, s74, v143
	ds_read_b128 v[176:179], v0
	ds_read_b128 v[180:183], v0 offset:1024
	ds_read_b128 v[190:193], v0 offset:2048
	ds_read_b128 v[194:197], v0 offset:3072
	s_add_i32 m0, s11, 0xc000
	ds_read_b128 v[198:201], v145
	ds_read_b128 v[202:205], v145 offset:1024
	ds_read_b128 v[206:209], v145 offset:2048
	ds_read_b128 v[210:213], v145 offset:3072
	ds_read_b128 v[214:217], v145 offset:4096
	ds_read_b128 v[218:221], v145 offset:5120
	ds_read_b128 v[222:225], v145 offset:6144
	ds_read_b128 v[226:229], v145 offset:7168
	global_load_lds_dwordx4 v138, s[20:21]
	s_add_i32 m0, s11, 0xe000
	s_nop 0
	global_load_lds_dwordx4 v140, s[20:21]
	s_waitcnt vmcnt(8)
	s_waitcnt lgkmcnt(0)
	s_barrier
	s_setprio 1
	v_mfma_f32_16x16x32_bf16 v[126:129], v[146:149], v[198:201], v[126:129]
	v_mfma_f32_16x16x32_bf16 v[122:125], v[154:157], v[198:201], v[122:125]
	v_mfma_f32_16x16x32_bf16 v[118:121], v[146:149], v[206:209], v[118:121]
	v_mfma_f32_16x16x32_bf16 v[114:117], v[154:157], v[206:209], v[114:117]
	v_mfma_f32_16x16x32_bf16 v[102:105], v[146:149], v[214:217], v[102:105]
	v_mfma_f32_16x16x32_bf16 v[98:101], v[154:157], v[214:217], v[98:101]
	v_mfma_f32_16x16x32_bf16 v[86:89], v[146:149], v[222:225], v[86:89]
	v_mfma_f32_16x16x32_bf16 v[82:85], v[154:157], v[222:225], v[82:85]
	v_mfma_f32_16x16x32_bf16 v[126:129], v[150:153], v[202:205], v[126:129]
	v_mfma_f32_16x16x32_bf16 v[122:125], v[158:161], v[202:205], v[122:125]
	v_mfma_f32_16x16x32_bf16 v[118:121], v[150:153], v[210:213], v[118:121]
	v_mfma_f32_16x16x32_bf16 v[114:117], v[158:161], v[210:213], v[114:117]
	v_mfma_f32_16x16x32_bf16 v[102:105], v[150:153], v[218:221], v[102:105]
	v_mfma_f32_16x16x32_bf16 v[98:101], v[158:161], v[218:221], v[98:101]
	v_mfma_f32_16x16x32_bf16 v[86:89], v[150:153], v[226:229], v[86:89]
	v_mfma_f32_16x16x32_bf16 v[82:85], v[158:161], v[226:229], v[82:85]
	v_mfma_f32_16x16x32_bf16 v[110:113], v[176:179], v[198:201], v[110:113]
	v_mfma_f32_16x16x32_bf16 v[106:109], v[190:193], v[198:201], v[106:109]
	v_mfma_f32_16x16x32_bf16 v[94:97], v[176:179], v[206:209], v[94:97]
	v_mfma_f32_16x16x32_bf16 v[90:93], v[190:193], v[206:209], v[90:93]
	v_mfma_f32_16x16x32_bf16 v[78:81], v[176:179], v[214:217], v[78:81]
	v_mfma_f32_16x16x32_bf16 v[74:77], v[190:193], v[214:217], v[74:77]
	v_mfma_f32_16x16x32_bf16 v[70:73], v[176:179], v[222:225], v[70:73]
	v_mfma_f32_16x16x32_bf16 v[66:69], v[190:193], v[222:225], v[66:69]
	v_mfma_f32_16x16x32_bf16 v[110:113], v[180:183], v[202:205], v[110:113]
	v_mfma_f32_16x16x32_bf16 v[106:109], v[194:197], v[202:205], v[106:109]
	v_mfma_f32_16x16x32_bf16 v[94:97], v[180:183], v[210:213], v[94:97]
	v_mfma_f32_16x16x32_bf16 v[90:93], v[194:197], v[210:213], v[90:93]
	v_mfma_f32_16x16x32_bf16 v[78:81], v[180:183], v[218:221], v[78:81]
	v_mfma_f32_16x16x32_bf16 v[74:77], v[194:197], v[218:221], v[74:77]
	v_mfma_f32_16x16x32_bf16 v[70:73], v[180:183], v[226:229], v[70:73]
	v_mfma_f32_16x16x32_bf16 v[66:69], v[194:197], v[226:229], v[66:69]
	s_setprio 0
	s_barrier
	s_add_i32 s72, s72, s40
	v_lshl_add_u64 v[162:163], s[22:23], 0, v[134:135]
	s_mov_b32 m0, s72
	ds_read_b128 v[198:201], v145 offset:16384
	ds_read_b128 v[202:205], v145 offset:17408
	ds_read_b128 v[206:209], v145 offset:18432
	ds_read_b128 v[210:213], v145 offset:19456
	ds_read_b128 v[214:217], v145 offset:20480
	ds_read_b128 v[218:221], v145 offset:21504
	ds_read_b128 v[222:225], v145 offset:22528
	ds_read_b128 v[226:229], v145 offset:23552
	global_load_lds_dwordx4 v[162:163], off
	s_add_i32 m0, s72, 0x2000
	s_add_u32 s72, s22, 0x40000
	v_lshl_add_u64 v[230:231], s[22:23], 0, v[130:131]
	s_addc_u32 s73, s23, 0
	s_add_i32 s74, s74, s40
	global_load_lds_dwordx4 v[230:231], off
	s_mov_b32 m0, s74
	v_lshl_add_u64 v[238:239], s[38:39], 0, v[132:133]
	global_load_lds_dwordx4 v134, s[72:73]
	s_add_i32 m0, s74, 0x2000
	s_nop 0
	global_load_lds_dwordx4 v130, s[72:73]
	v_lshl_add_u64 v[236:237], s[38:39], 0, v[136:137]
	s_mov_b32 m0, s11
	s_nop 0
	global_load_lds_dwordx4 v[236:237], off
	s_mov_b32 m0, s41
	s_nop 0
	global_load_lds_dwordx4 v[238:239], off
	s_waitcnt vmcnt(8)
	s_waitcnt lgkmcnt(0)
	s_barrier
; #define PG8_STAGE(bufoff, gbase, voff) do { _Pragma("unroll") for (int _i = 0; _i < 2; ++_i) \
;         __builtin_amdgcn_global_load_lds((const unsigned*)((const char*)(gbase) + (voff)[_i]), (LAS unsigned*)(lds + (bufoff) + ldsw + _i * 8192), 16, 0, 0); } while (0)
; #define PG8_LDA(dst, b, h) do { _Pragma("unroll") for (int m = 0; m < 4; ++m) _Pragma("unroll") for (int k = 0; k < 2; ++k) dst[m][k] = *(const LAS bf16x8*)(lds + PG8_SA(b, h) + aoff + m * 2048 + k * 1024); } while (0)
; #define PG8_LDB(dst, b, h) do { _Pragma("unroll") for (int n = 0; n < 2; ++n) _Pragma("unroll") for (int k = 0; k < 2; ++k) dst[n][k] = *(const LAS bf16x8*)(lds + PG8_SB(b, h) + boff + n * 2048 + k * 1024); } while (0)
; #define PG8_MMA(ai, bj, At, Bt) do { __builtin_amdgcn_s_setprio(1); _Pragma("unroll") for (int m = 0; m < 4; ++m) _Pragma("unroll") for (int n = 0; n < 2; ++n) _Pragma("unroll") for (int k = 0; k < 2; ++k) \
;         acc[ai][bj][m][n] = __builtin_amdgcn_mfma_f32_16x16x32_bf16(Bt[n][k], At[m][k], acc[ai][bj][m][n], 0, 0, 0); __builtin_amdgcn_s_setprio(0); } while (0)
; #define PG8_WAIT_V(n) asm volatile("s_waitcnt vmcnt(" #n ")" ::: "memory")
; #define PG8_WAIT_L(n) asm volatile("s_waitcnt lgkmcnt(" #n ")" ::: "memory")
; #define PG8_BAR __builtin_amdgcn_s_barrier()
; #define PG8_SCHED __builtin_amdgcn_sched_barrier(0)
; template <class Epi>
; DI void gemm_phase(int wid0, LAS unsigned char* lds, const Gemm g, const StaticOrder& S, const Epi& E) {
;     ...
;             PG8_WAIT_V(8); PG8_WAIT_L(0); PG8_BAR; PG8_MMA(1, 0, At, B0); PG8_MMA(1, 1, At, B1); PG8_BAR; PG8_SCHED;
;             PG8_LDB(B0, 1, 0); PG8_LDB(B1, 1, 1); PG8_SCHED; PG8_LDA(At, 1, 0); PG8_STAGE(PG8_SA(0, 1), a2 + hstep, voffA);
;             PG8_WAIT_V(8); PG8_WAIT_L(0); PG8_BAR; PG8_MMA(0, 0, At, B0); PG8_MMA(0, 1, At, B1); PG8_BAR; PG8_SCHED;
	s_setprio 1
	v_mfma_f32_16x16x32_bf16 v[62:65], v[146:149], v[198:201], v[62:65]
	v_mfma_f32_16x16x32_bf16 v[58:61], v[154:157], v[198:201], v[58:61]
	v_mfma_f32_16x16x32_bf16 v[54:57], v[146:149], v[206:209], v[54:57]
	v_mfma_f32_16x16x32_bf16 v[50:53], v[154:157], v[206:209], v[50:53]
	v_mfma_f32_16x16x32_bf16 v[38:41], v[146:149], v[214:217], v[38:41]
	v_mfma_f32_16x16x32_bf16 v[34:37], v[154:157], v[214:217], v[34:37]
	v_mfma_f32_16x16x32_bf16 v[22:25], v[146:149], v[222:225], v[22:25]
	v_mfma_f32_16x16x32_bf16 v[18:21], v[154:157], v[222:225], v[18:21]
	v_mfma_f32_16x16x32_bf16 v[62:65], v[150:153], v[202:205], v[62:65]
	v_mfma_f32_16x16x32_bf16 v[58:61], v[158:161], v[202:205], v[58:61]
	v_mfma_f32_16x16x32_bf16 v[54:57], v[150:153], v[210:213], v[54:57]
	v_mfma_f32_16x16x32_bf16 v[50:53], v[158:161], v[210:213], v[50:53]
	v_mfma_f32_16x16x32_bf16 v[38:41], v[150:153], v[218:221], v[38:41]
	v_mfma_f32_16x16x32_bf16 v[34:37], v[158:161], v[218:221], v[34:37]
	v_mfma_f32_16x16x32_bf16 v[22:25], v[150:153], v[226:229], v[22:25]
	v_mfma_f32_16x16x32_bf16 v[18:21], v[158:161], v[226:229], v[18:21]
	v_mfma_f32_16x16x32_bf16 v[46:49], v[176:179], v[198:201], v[46:49]
	v_mfma_f32_16x16x32_bf16 v[42:45], v[190:193], v[198:201], v[42:45]
	v_mfma_f32_16x16x32_bf16 v[30:33], v[176:179], v[206:209], v[30:33]
	v_mfma_f32_16x16x32_bf16 v[26:29], v[190:193], v[206:209], v[26:29]
	v_mfma_f32_16x16x32_bf16 v[14:17], v[176:179], v[214:217], v[14:17]
	v_mfma_f32_16x16x32_bf16 v[10:13], v[190:193], v[214:217], v[10:13]
	v_mfma_f32_16x16x32_bf16 v[6:9], v[176:179], v[222:225], v[6:9]
	v_mfma_f32_16x16x32_bf16 v[2:5], v[190:193], v[222:225], v[2:5]
	v_mfma_f32_16x16x32_bf16 v[46:49], v[180:183], v[202:205], v[46:49]
	v_mfma_f32_16x16x32_bf16 v[42:45], v[194:197], v[202:205], v[42:45]
	v_mfma_f32_16x16x32_bf16 v[30:33], v[180:183], v[210:213], v[30:33]
	v_mfma_f32_16x16x32_bf16 v[26:29], v[194:197], v[210:213], v[26:29]
	v_mfma_f32_16x16x32_bf16 v[14:17], v[180:183], v[218:221], v[14:17]
	v_mfma_f32_16x16x32_bf16 v[10:13], v[194:197], v[218:221], v[10:13]
	v_mfma_f32_16x16x32_bf16 v[6:9], v[180:183], v[226:229], v[6:9]
	v_mfma_f32_16x16x32_bf16 v[2:5], v[194:197], v[226:229], v[2:5]
	s_setprio 0
	s_barrier
	s_add_i32 s72, 0, 0x18000
	v_add_u32_e32 v0, s72, v143
	s_add_i32 s73, 0, 0x1c000
	ds_read_b128 v[146:149], v0
	ds_read_b128 v[150:153], v0 offset:1024
	ds_read_b128 v[154:157], v0 offset:2048
	ds_read_b128 v[158:161], v0 offset:3072
	v_add_u32_e32 v0, s73, v143
	ds_read_b128 v[176:179], v0
	ds_read_b128 v[180:183], v0 offset:1024
	ds_read_b128 v[190:193], v0 offset:2048
	ds_read_b128 v[194:197], v0 offset:3072
	s_add_u32 s38, s38, 0x40000
	s_addc_u32 s39, s39, 0
	s_mov_b32 m0, s46
	ds_read_b128 v[198:201], v145 offset:32768
	ds_read_b128 v[202:205], v145 offset:33792
	ds_read_b128 v[206:209], v145 offset:34816
	ds_read_b128 v[210:213], v145 offset:35840
	ds_read_b128 v[214:217], v145 offset:36864
	ds_read_b128 v[218:221], v145 offset:37888
	ds_read_b128 v[222:225], v145 offset:38912
	ds_read_b128 v[226:229], v145 offset:39936
	global_load_lds_dwordx4 v136, s[38:39]
	v_lshl_add_u64 v[240:241], s[38:39], 0, v[132:133]
	s_mov_b32 m0, s47
	s_nop 0
	global_load_lds_dwordx4 v[240:241], off
	s_waitcnt vmcnt(8)
	s_waitcnt lgkmcnt(0)
	s_barrier
	s_setprio 1
	v_mfma_f32_16x16x32_bf16 v[126:129], v[146:149], v[198:201], v[126:129]
	v_mfma_f32_16x16x32_bf16 v[122:125], v[154:157], v[198:201], v[122:125]
	v_mfma_f32_16x16x32_bf16 v[118:121], v[146:149], v[206:209], v[118:121]
	v_mfma_f32_16x16x32_bf16 v[114:117], v[154:157], v[206:209], v[114:117]
	v_mfma_f32_16x16x32_bf16 v[102:105], v[146:149], v[214:217], v[102:105]
	v_mfma_f32_16x16x32_bf16 v[98:101], v[154:157], v[214:217], v[98:101]
	v_mfma_f32_16x16x32_bf16 v[86:89], v[146:149], v[222:225], v[86:89]
	v_mfma_f32_16x16x32_bf16 v[82:85], v[154:157], v[222:225], v[82:85]
	v_mfma_f32_16x16x32_bf16 v[126:129], v[150:153], v[202:205], v[126:129]
	v_mfma_f32_16x16x32_bf16 v[122:125], v[158:161], v[202:205], v[122:125]
	v_mfma_f32_16x16x32_bf16 v[118:121], v[150:153], v[210:213], v[118:121]
	v_mfma_f32_16x16x32_bf16 v[114:117], v[158:161], v[210:213], v[114:117]
	v_mfma_f32_16x16x32_bf16 v[102:105], v[150:153], v[218:221], v[102:105]
	v_mfma_f32_16x16x32_bf16 v[98:101], v[158:161], v[218:221], v[98:101]
	v_mfma_f32_16x16x32_bf16 v[86:89], v[150:153], v[226:229], v[86:89]
	v_mfma_f32_16x16x32_bf16 v[82:85], v[158:161], v[226:229], v[82:85]
	v_mfma_f32_16x16x32_bf16 v[110:113], v[176:179], v[198:201], v[110:113]
	v_mfma_f32_16x16x32_bf16 v[106:109], v[190:193], v[198:201], v[106:109]
	v_mfma_f32_16x16x32_bf16 v[94:97], v[176:179], v[206:209], v[94:97]
	v_mfma_f32_16x16x32_bf16 v[90:93], v[190:193], v[206:209], v[90:93]
	v_mfma_f32_16x16x32_bf16 v[78:81], v[176:179], v[214:217], v[78:81]
	v_mfma_f32_16x16x32_bf16 v[74:77], v[190:193], v[214:217], v[74:77]
	v_mfma_f32_16x16x32_bf16 v[70:73], v[176:179], v[222:225], v[70:73]
	v_mfma_f32_16x16x32_bf16 v[66:69], v[190:193], v[222:225], v[66:69]
	v_mfma_f32_16x16x32_bf16 v[110:113], v[180:183], v[202:205], v[110:113]
	v_mfma_f32_16x16x32_bf16 v[106:109], v[194:197], v[202:205], v[106:109]
	v_mfma_f32_16x16x32_bf16 v[94:97], v[180:183], v[210:213], v[94:97]
	v_mfma_f32_16x16x32_bf16 v[90:93], v[194:197], v[210:213], v[90:93]
	v_mfma_f32_16x16x32_bf16 v[78:81], v[180:183], v[218:221], v[78:81]
	v_mfma_f32_16x16x32_bf16 v[74:77], v[194:197], v[218:221], v[74:77]
	v_mfma_f32_16x16x32_bf16 v[70:73], v[180:183], v[226:229], v[70:73]
	v_mfma_f32_16x16x32_bf16 v[66:69], v[194:197], v[226:229], v[66:69]
	s_setprio 0
	s_barrier
; #define PG8_STAGE(bufoff, gbase, voff) do { _Pragma("unroll") for (int _i = 0; _i < 2; ++_i) \
;         __builtin_amdgcn_global_load_lds((const unsigned*)((const char*)(gbase) + (voff)[_i]), (LAS unsigned*)(lds + (bufoff) + ldsw + _i * 8192), 16, 0, 0); } while (0)
; #define PG8_LDA(dst, b, h) do { _Pragma("unroll") for (int m = 0; m < 4; ++m) _Pragma("unroll") for (int k = 0; k < 2; ++k) dst[m][k] = *(const LAS bf16x8*)(lds + PG8_SA(b, h) + aoff + m * 2048 + k * 1024); } while (0)
; #define PG8_MMA(ai, bj, At, Bt) do { __builtin_amdgcn_s_setprio(1); _Pragma("unroll") for (int m = 0; m < 4; ++m) _Pragma("unroll") for (int n = 0; n < 2; ++n) _Pragma("unroll") for (int k = 0; k < 2; ++k) \
;         acc[ai][bj][m][n] = __builtin_amdgcn_mfma_f32_16x16x32_bf16(Bt[n][k], At[m][k], acc[ai][bj][m][n], 0, 0, 0); __builtin_amdgcn_s_setprio(0); } while (0)
; #define PG8_WAIT_V(n) asm volatile("s_waitcnt vmcnt(" #n ")" ::: "memory")
; #define PG8_WAIT_L(n) asm volatile("s_waitcnt lgkmcnt(" #n ")" ::: "memory")
; #define PG8_BAR __builtin_amdgcn_s_barrier()
; #define PG8_SCHED __builtin_amdgcn_sched_barrier(0)
; template <class Epi>
; DI void gemm_phase(int wid0, LAS unsigned char* lds, const Gemm g, const StaticOrder& S, const Epi& E) {
;     ...
;             PG8_LDA(At, 1, 1); PG8_STAGE(PG8_SB(1, 0), b3, voffB); PG8_STAGE(PG8_SB(1, 1), b3 + hstep, voffB); PG8_STAGE(PG8_SA(1, 0), a3, voffA);
;             PG8_WAIT_V(8); PG8_WAIT_L(0); PG8_BAR; PG8_MMA(1, 0, At, B0); PG8_MMA(1, 1, At, B1); PG8_BAR; PG8_SCHED;
;         }
;         if (wr == 0) PG8_BAR;
	s_add_i32 s38, s72, s40
	v_lshl_add_u64 v[162:163], v[162:163], 0, s[30:31]
	s_mov_b32 m0, s38
	ds_read_b128 v[198:201], v145 offset:49152
	ds_read_b128 v[202:205], v145 offset:50176
	ds_read_b128 v[206:209], v145 offset:51200
	ds_read_b128 v[210:213], v145 offset:52224
	ds_read_b128 v[214:217], v145 offset:53248
	ds_read_b128 v[218:221], v145 offset:54272
	ds_read_b128 v[222:225], v145 offset:55296
	ds_read_b128 v[226:229], v145 offset:56320
	global_load_lds_dwordx4 v[162:163], off
	s_add_i32 m0, s38, 0x2000
	s_add_u32 s22, s22, 0x40080
	v_lshl_add_u64 v[162:163], v[230:231], 0, s[30:31]
	s_addc_u32 s23, s23, 0
	s_add_i32 s38, s73, s40
	global_load_lds_dwordx4 v[162:163], off
	s_mov_b32 m0, s38
	s_nop 0
	global_load_lds_dwordx4 v134, s[22:23]
	s_add_i32 m0, s38, 0x2000
	s_nop 0
	global_load_lds_dwordx4 v130, s[22:23]
	v_lshl_add_u64 v[162:163], v[236:237], 0, s[30:31]
	s_mov_b32 m0, s2
	s_nop 0
	global_load_lds_dwordx4 v[162:163], off
	v_lshl_add_u64 v[162:163], v[238:239], 0, s[30:31]
	s_mov_b32 m0, s48
	s_nop 0
	global_load_lds_dwordx4 v[162:163], off
	s_waitcnt vmcnt(8)
	s_waitcnt lgkmcnt(0)
	s_barrier
	s_setprio 1
	v_mfma_f32_16x16x32_bf16 v[62:65], v[146:149], v[198:201], v[62:65]
	v_mfma_f32_16x16x32_bf16 v[58:61], v[154:157], v[198:201], v[58:61]
	v_mfma_f32_16x16x32_bf16 v[54:57], v[146:149], v[206:209], v[54:57]
	v_mfma_f32_16x16x32_bf16 v[50:53], v[154:157], v[206:209], v[50:53]
	v_mfma_f32_16x16x32_bf16 v[38:41], v[146:149], v[214:217], v[38:41]
	v_mfma_f32_16x16x32_bf16 v[34:37], v[154:157], v[214:217], v[34:37]
	v_mfma_f32_16x16x32_bf16 v[22:25], v[146:149], v[222:225], v[22:25]
	v_mfma_f32_16x16x32_bf16 v[18:21], v[154:157], v[222:225], v[18:21]
	v_mfma_f32_16x16x32_bf16 v[62:65], v[150:153], v[202:205], v[62:65]
	v_mfma_f32_16x16x32_bf16 v[58:61], v[158:161], v[202:205], v[58:61]
	v_mfma_f32_16x16x32_bf16 v[54:57], v[150:153], v[210:213], v[54:57]
	v_mfma_f32_16x16x32_bf16 v[50:53], v[158:161], v[210:213], v[50:53]
	v_mfma_f32_16x16x32_bf16 v[38:41], v[150:153], v[218:221], v[38:41]
	v_mfma_f32_16x16x32_bf16 v[34:37], v[158:161], v[218:221], v[34:37]
	v_mfma_f32_16x16x32_bf16 v[22:25], v[150:153], v[226:229], v[22:25]
	v_mfma_f32_16x16x32_bf16 v[18:21], v[158:161], v[226:229], v[18:21]
	v_mfma_f32_16x16x32_bf16 v[46:49], v[176:179], v[198:201], v[46:49]
	v_mfma_f32_16x16x32_bf16 v[42:45], v[190:193], v[198:201], v[42:45]
	v_mfma_f32_16x16x32_bf16 v[30:33], v[176:179], v[206:209], v[30:33]
	v_mfma_f32_16x16x32_bf16 v[26:29], v[190:193], v[206:209], v[26:29]
	v_mfma_f32_16x16x32_bf16 v[14:17], v[176:179], v[214:217], v[14:17]
	v_mfma_f32_16x16x32_bf16 v[10:13], v[190:193], v[214:217], v[10:13]
	v_mfma_f32_16x16x32_bf16 v[6:9], v[176:179], v[222:225], v[6:9]
	v_mfma_f32_16x16x32_bf16 v[2:5], v[190:193], v[222:225], v[2:5]
	v_mfma_f32_16x16x32_bf16 v[46:49], v[180:183], v[202:205], v[46:49]
	v_mfma_f32_16x16x32_bf16 v[42:45], v[194:197], v[202:205], v[42:45]
	v_mfma_f32_16x16x32_bf16 v[30:33], v[180:183], v[210:213], v[30:33]
	v_mfma_f32_16x16x32_bf16 v[26:29], v[194:197], v[210:213], v[26:29]
	v_mfma_f32_16x16x32_bf16 v[14:17], v[180:183], v[218:221], v[14:17]
	v_mfma_f32_16x16x32_bf16 v[10:13], v[194:197], v[218:221], v[10:13]
	v_mfma_f32_16x16x32_bf16 v[6:9], v[180:183], v[226:229], v[6:9]
	v_mfma_f32_16x16x32_bf16 v[2:5], v[194:197], v[226:229], v[2:5]
	s_setprio 0
	s_barrier
	s_add_i32 s71, s71, 2
	s_add_u32 s20, s20, 0x100
	s_addc_u32 s21, s21, 0
	s_add_u32 s69, s69, 0x100
	s_addc_u32 s70, s70, 0
	s_cmp_gt_u32 s71, 13
	s_cbranch_scc0 .LBB0_139
	s_and_b64 vcc, exec, s[8:9]
	s_cbranch_vccz .LBB0_142
	s_barrier

; #define PG8_STAGE(bufoff, gbase, voff) do { _Pragma("unroll") for (int _i = 0; _i < 2; ++_i) \
;         __builtin_amdgcn_global_load_lds((const unsigned*)((const char*)(gbase) + (voff)[_i]), (LAS unsigned*)(lds + (bufoff) + ldsw + _i * 8192), 16, 0, 0); } while (0)
; #define PG8_LDA(dst, b, h) do { _Pragma("unroll") for (int m = 0; m < 4; ++m) _Pragma("unroll") for (int k = 0; k < 2; ++k) dst[m][k] = *(const LAS bf16x8*)(lds + PG8_SA(b, h) + aoff + m * 2048 + k * 1024); } while (0)
; #define PG8_LDB(dst, b, h) do { _Pragma("unroll") for (int n = 0; n < 2; ++n) _Pragma("unroll") for (int k = 0; k < 2; ++k) dst[n][k] = *(const LAS bf16x8*)(lds + PG8_SB(b, h) + boff + n * 2048 + k * 1024); } while (0)
; #define PG8_MMA(ai, bj, At, Bt) do { __builtin_amdgcn_s_setprio(1); _Pragma("unroll") for (int m = 0; m < 4; ++m) _Pragma("unroll") for (int n = 0; n < 2; ++n) _Pragma("unroll") for (int k = 0; k < 2; ++k) \
;         acc[ai][bj][m][n] = __builtin_amdgcn_mfma_f32_16x16x32_bf16(Bt[n][k], At[m][k], acc[ai][bj][m][n], 0, 0, 0); __builtin_amdgcn_s_setprio(0); } while (0)
; #define PG8_WAIT_V(n) asm volatile("s_waitcnt vmcnt(" #n ")" ::: "memory")
; #define PG8_BAR __builtin_amdgcn_s_barrier()
; template <class Epi>
; DI void gemm_phase(int wid0, LAS unsigned char* lds, const Gemm g, const StaticOrder& S, const Epi& E) {
;     ...
;         const char* nA = has_next ? (const char*)g.A + (size_t)nxt.pm * tstep : cA; const char* nB = has_next ? (const char*)g.Bt + (size_t)nxt.pn * tstep : cB;
;         for (int t = 0; t < nt; t += 2) {
;             const bool last = (t == nt - 2);
;             const char* a1 = cA + (size_t)(t + 1) * kstep;
;             const char* a2 = last ? nA : cA + (size_t)(t + 2) * kstep; const char* b2 = last ? nB : cB + (size_t)(t + 2) * kstep;
;             const char* a3 = a2 + kstep; const char* b3 = b2 + kstep;
;             PG8_LDB(B0, 0, 0); PG8_LDB(B1, 0, 1); PG8_SCHED; PG8_LDA(At, 0, 0); PG8_STAGE(PG8_SA(1, 1), a1 + hstep, voffA);
;             PG8_WAIT_V(8); PG8_WAIT_L(0); PG8_BAR; PG8_MMA(0, 0, At, B0); PG8_MMA(0, 1, At, B1); PG8_BAR; PG8_SCHED;
;             PG8_LDA(At, 0, 1); PG8_STAGE(PG8_SB(0, 0), b2, voffB); PG8_STAGE(PG8_SB(0, 1), b2 + hstep, voffB); PG8_STAGE(PG8_SA(0, 0), a2, voffA);
;             PG8_WAIT_V(8); PG8_WAIT_L(0); PG8_BAR; PG8_MMA(1, 0, At, B0); PG8_MMA(1, 1, At, B1); PG8_BAR; PG8_SCHED;
.LBB0_207:
	s_add_u32 s46, s44, 0xfff80080
	s_addc_u32 s47, s45, -1
	s_add_i32 s72, 0, 0x10000
	s_cmp_eq_u32 s71, 28
	s_cselect_b32 s49, s19, s47
	s_cselect_b32 s48, s66, s46
	v_add_u32_e32 v144, s72, v147
	s_cselect_b32 s47, s17, s70
	s_cselect_b32 s46, s67, s69
	s_add_i32 s74, 0, 0x14000
	ds_read_b128 v[140:143], v144
	ds_read_b128 v[150:153], v144 offset:1024
	ds_read_b128 v[154:157], v144 offset:2048
	ds_read_b128 v[158:161], v144 offset:3072
	v_add_u32_e32 v144, s74, v147
	ds_read_b128 v[176:179], v144
	ds_read_b128 v[180:183], v144 offset:1024
	ds_read_b128 v[190:193], v144 offset:2048
	ds_read_b128 v[194:197], v144 offset:3072
	s_add_i32 m0, s41, 0xc000
	ds_read_b128 v[198:201], v149
	ds_read_b128 v[202:205], v149 offset:1024
	ds_read_b128 v[206:209], v149 offset:2048
	ds_read_b128 v[210:213], v149 offset:3072
	ds_read_b128 v[214:217], v149 offset:4096
	ds_read_b128 v[218:221], v149 offset:5120
	ds_read_b128 v[222:225], v149 offset:6144
	ds_read_b128 v[226:229], v149 offset:7168
	global_load_lds_dwordx4 v136, s[44:45]
	s_add_i32 m0, s41, 0xe000
	s_nop 0
	global_load_lds_dwordx4 v138, s[44:45]
	s_waitcnt vmcnt(8)
	s_waitcnt lgkmcnt(0)
	s_barrier
	s_setprio 1
	v_mfma_f32_16x16x32_bf16 v[126:129], v[140:143], v[198:201], v[126:129]
	v_mfma_f32_16x16x32_bf16 v[122:125], v[154:157], v[198:201], v[122:125]
	v_mfma_f32_16x16x32_bf16 v[110:113], v[140:143], v[206:209], v[110:113]
	v_mfma_f32_16x16x32_bf16 v[106:109], v[154:157], v[206:209], v[106:109]
	v_mfma_f32_16x16x32_bf16 v[94:97], v[140:143], v[214:217], v[94:97]
	v_mfma_f32_16x16x32_bf16 v[90:93], v[154:157], v[214:217], v[90:93]
	v_mfma_f32_16x16x32_bf16 v[78:81], v[140:143], v[222:225], v[78:81]
	v_mfma_f32_16x16x32_bf16 v[74:77], v[154:157], v[222:225], v[74:77]
	v_mfma_f32_16x16x32_bf16 v[126:129], v[150:153], v[202:205], v[126:129]
	v_mfma_f32_16x16x32_bf16 v[122:125], v[158:161], v[202:205], v[122:125]
	v_mfma_f32_16x16x32_bf16 v[110:113], v[150:153], v[210:213], v[110:113]
	v_mfma_f32_16x16x32_bf16 v[106:109], v[158:161], v[210:213], v[106:109]
	v_mfma_f32_16x16x32_bf16 v[94:97], v[150:153], v[218:221], v[94:97]
	v_mfma_f32_16x16x32_bf16 v[90:93], v[158:161], v[218:221], v[90:93]
	v_mfma_f32_16x16x32_bf16 v[78:81], v[150:153], v[226:229], v[78:81]
	v_mfma_f32_16x16x32_bf16 v[74:77], v[158:161], v[226:229], v[74:77]
	v_mfma_f32_16x16x32_bf16 v[118:121], v[176:179], v[198:201], v[118:121]
	v_mfma_f32_16x16x32_bf16 v[114:117], v[190:193], v[198:201], v[114:117]
	v_mfma_f32_16x16x32_bf16 v[102:105], v[176:179], v[206:209], v[102:105]
	v_mfma_f32_16x16x32_bf16 v[98:101], v[190:193], v[206:209], v[98:101]
	v_mfma_f32_16x16x32_bf16 v[86:89], v[176:179], v[214:217], v[86:89]
	v_mfma_f32_16x16x32_bf16 v[82:85], v[190:193], v[214:217], v[82:85]
	v_mfma_f32_16x16x32_bf16 v[70:73], v[176:179], v[222:225], v[70:73]
	v_mfma_f32_16x16x32_bf16 v[66:69], v[190:193], v[222:225], v[66:69]
	v_mfma_f32_16x16x32_bf16 v[118:121], v[180:183], v[202:205], v[118:121]
	v_mfma_f32_16x16x32_bf16 v[114:117], v[194:197], v[202:205], v[114:117]
	v_mfma_f32_16x16x32_bf16 v[102:105], v[180:183], v[210:213], v[102:105]
	v_mfma_f32_16x16x32_bf16 v[98:101], v[194:197], v[210:213], v[98:101]
	v_mfma_f32_16x16x32_bf16 v[86:89], v[180:183], v[218:221], v[86:89]
	v_mfma_f32_16x16x32_bf16 v[82:85], v[194:197], v[218:221], v[82:85]
	v_mfma_f32_16x16x32_bf16 v[70:73], v[180:183], v[226:229], v[70:73]
	v_mfma_f32_16x16x32_bf16 v[66:69], v[194:197], v[226:229], v[66:69]
	s_setprio 0
	s_barrier
	s_add_i32 s72, s72, s40
	v_lshl_add_u64 v[144:145], s[46:47], 0, v[0:1]
	s_mov_b32 m0, s72
	ds_read_b128 v[198:201], v149 offset:16384
	ds_read_b128 v[202:205], v149 offset:17408
	ds_read_b128 v[206:209], v149 offset:18432
	ds_read_b128 v[210:213], v149 offset:19456
	ds_read_b128 v[214:217], v149 offset:20480
	ds_read_b128 v[218:221], v149 offset:21504
	ds_read_b128 v[222:225], v149 offset:22528
	ds_read_b128 v[226:229], v149 offset:23552
	global_load_lds_dwordx4 v[144:145], off
	s_add_i32 m0, s72, 0x2000
	s_add_u32 s72, s46, 0x80000
	v_lshl_add_u64 v[162:163], s[46:47], 0, v[130:131]
	s_addc_u32 s73, s47, 0
	s_add_i32 s74, s74, s40
	global_load_lds_dwordx4 v[162:163], off
	v_lshl_add_u64 v[230:231], s[72:73], 0, v[0:1]
	s_mov_b32 m0, s74
	v_lshl_add_u64 v[236:237], s[48:49], 0, v[132:133]
	global_load_lds_dwordx4 v[230:231], off
	s_add_i32 m0, s74, 0x2000
	s_nop 0
	global_load_lds_dwordx4 v130, s[72:73]
	v_lshl_add_u64 v[230:231], s[48:49], 0, v[134:135]
	s_mov_b32 m0, s41
	s_nop 0
	global_load_lds_dwordx4 v[230:231], off
	s_mov_b32 m0, s50
	s_nop 0
	global_load_lds_dwordx4 v[236:237], off
	s_waitcnt vmcnt(8)
	s_waitcnt lgkmcnt(0)
	s_barrier
; #define PG8_STAGE(bufoff, gbase, voff) do { _Pragma("unroll") for (int _i = 0; _i < 2; ++_i) \
;         __builtin_amdgcn_global_load_lds((const unsigned*)((const char*)(gbase) + (voff)[_i]), (LAS unsigned*)(lds + (bufoff) + ldsw + _i * 8192), 16, 0, 0); } while (0)
; #define PG8_LDA(dst, b, h) do { _Pragma("unroll") for (int m = 0; m < 4; ++m) _Pragma("unroll") for (int k = 0; k < 2; ++k) dst[m][k] = *(const LAS bf16x8*)(lds + PG8_SA(b, h) + aoff + m * 2048 + k * 1024); } while (0)
; #define PG8_LDB(dst, b, h) do { _Pragma("unroll") for (int n = 0; n < 2; ++n) _Pragma("unroll") for (int k = 0; k < 2; ++k) dst[n][k] = *(const LAS bf16x8*)(lds + PG8_SB(b, h) + boff + n * 2048 + k * 1024); } while (0)
; #define PG8_MMA(ai, bj, At, Bt) do { __builtin_amdgcn_s_setprio(1); _Pragma("unroll") for (int m = 0; m < 4; ++m) _Pragma("unroll") for (int n = 0; n < 2; ++n) _Pragma("unroll") for (int k = 0; k < 2; ++k) \
;         acc[ai][bj][m][n] = __builtin_amdgcn_mfma_f32_16x16x32_bf16(Bt[n][k], At[m][k], acc[ai][bj][m][n], 0, 0, 0); __builtin_amdgcn_s_setprio(0); } while (0)
; #define PG8_WAIT_V(n) asm volatile("s_waitcnt vmcnt(" #n ")" ::: "memory")
; #define PG8_WAIT_L(n) asm volatile("s_waitcnt lgkmcnt(" #n ")" ::: "memory")
; #define PG8_BAR __builtin_amdgcn_s_barrier()
; #define PG8_SCHED __builtin_amdgcn_sched_barrier(0)
; template <class Epi>
; DI void gemm_phase(int wid0, LAS unsigned char* lds, const Gemm g, const StaticOrder& S, const Epi& E) {
;     ...
;             PG8_WAIT_V(8); PG8_WAIT_L(0); PG8_BAR; PG8_MMA(1, 0, At, B0); PG8_MMA(1, 1, At, B1); PG8_BAR; PG8_SCHED;
;             PG8_LDB(B0, 1, 0); PG8_LDB(B1, 1, 1); PG8_SCHED; PG8_LDA(At, 1, 0); PG8_STAGE(PG8_SA(0, 1), a2 + hstep, voffA);
;             PG8_WAIT_V(8); PG8_WAIT_L(0); PG8_BAR; PG8_MMA(0, 0, At, B0); PG8_MMA(0, 1, At, B1); PG8_BAR; PG8_SCHED;
	s_setprio 1
	v_mfma_f32_16x16x32_bf16 v[62:65], v[140:143], v[198:201], v[62:65]
	v_mfma_f32_16x16x32_bf16 v[58:61], v[154:157], v[198:201], v[58:61]
	v_mfma_f32_16x16x32_bf16 v[46:49], v[140:143], v[206:209], v[46:49]
	v_mfma_f32_16x16x32_bf16 v[42:45], v[154:157], v[206:209], v[42:45]
	v_mfma_f32_16x16x32_bf16 v[30:33], v[140:143], v[214:217], v[30:33]
	v_mfma_f32_16x16x32_bf16 v[26:29], v[154:157], v[214:217], v[26:29]
	v_mfma_f32_16x16x32_bf16 v[14:17], v[140:143], v[222:225], v[14:17]
	v_mfma_f32_16x16x32_bf16 v[10:13], v[154:157], v[222:225], v[10:13]
	v_mfma_f32_16x16x32_bf16 v[62:65], v[150:153], v[202:205], v[62:65]
	v_mfma_f32_16x16x32_bf16 v[58:61], v[158:161], v[202:205], v[58:61]
	v_mfma_f32_16x16x32_bf16 v[46:49], v[150:153], v[210:213], v[46:49]
	v_mfma_f32_16x16x32_bf16 v[42:45], v[158:161], v[210:213], v[42:45]
	v_mfma_f32_16x16x32_bf16 v[30:33], v[150:153], v[218:221], v[30:33]
	v_mfma_f32_16x16x32_bf16 v[26:29], v[158:161], v[218:221], v[26:29]
	v_mfma_f32_16x16x32_bf16 v[14:17], v[150:153], v[226:229], v[14:17]
	v_mfma_f32_16x16x32_bf16 v[10:13], v[158:161], v[226:229], v[10:13]
	v_mfma_f32_16x16x32_bf16 v[54:57], v[176:179], v[198:201], v[54:57]
	v_mfma_f32_16x16x32_bf16 v[50:53], v[190:193], v[198:201], v[50:53]
	v_mfma_f32_16x16x32_bf16 v[38:41], v[176:179], v[206:209], v[38:41]
	v_mfma_f32_16x16x32_bf16 v[34:37], v[190:193], v[206:209], v[34:37]
	v_mfma_f32_16x16x32_bf16 v[22:25], v[176:179], v[214:217], v[22:25]
	v_mfma_f32_16x16x32_bf16 v[18:21], v[190:193], v[214:217], v[18:21]
	v_mfma_f32_16x16x32_bf16 v[6:9], v[176:179], v[222:225], v[6:9]
	v_mfma_f32_16x16x32_bf16 v[2:5], v[190:193], v[222:225], v[2:5]
	v_mfma_f32_16x16x32_bf16 v[54:57], v[180:183], v[202:205], v[54:57]
	v_mfma_f32_16x16x32_bf16 v[50:53], v[194:197], v[202:205], v[50:53]
	v_mfma_f32_16x16x32_bf16 v[38:41], v[180:183], v[210:213], v[38:41]
	v_mfma_f32_16x16x32_bf16 v[34:37], v[194:197], v[210:213], v[34:37]
	v_mfma_f32_16x16x32_bf16 v[22:25], v[180:183], v[218:221], v[22:25]
	v_mfma_f32_16x16x32_bf16 v[18:21], v[194:197], v[218:221], v[18:21]
	v_mfma_f32_16x16x32_bf16 v[6:9], v[180:183], v[226:229], v[6:9]
	v_mfma_f32_16x16x32_bf16 v[2:5], v[194:197], v[226:229], v[2:5]
	s_setprio 0
	s_barrier
	s_add_i32 s72, 0, 0x18000
	s_add_i32 s73, 0, 0x1c000
	v_add_u32_e32 v158, s72, v147
	v_add_u32_e32 v189, s73, v147
	ds_read_b128 v[140:143], v158
	ds_read_b128 v[150:153], v158 offset:1024
	ds_read_b128 v[154:157], v158 offset:2048
	ds_read_b128 v[158:161], v158 offset:3072
	ds_read_b128 v[176:179], v189
	ds_read_b128 v[180:183], v189 offset:1024
	ds_read_b128 v[190:193], v189 offset:2048
	ds_read_b128 v[194:197], v189 offset:3072
	s_add_u32 s48, s48, 0x80000
	s_addc_u32 s49, s49, 0
	s_mov_b32 m0, s51
	ds_read_b128 v[198:201], v149 offset:32768
	ds_read_b128 v[202:205], v149 offset:33792
	ds_read_b128 v[206:209], v149 offset:34816
	ds_read_b128 v[210:213], v149 offset:35840
	ds_read_b128 v[214:217], v149 offset:36864
	ds_read_b128 v[218:221], v149 offset:37888
	ds_read_b128 v[222:225], v149 offset:38912
	ds_read_b128 v[226:229], v149 offset:39936
	global_load_lds_dwordx4 v134, s[48:49]
	v_lshl_add_u64 v[238:239], s[48:49], 0, v[132:133]
	s_mov_b32 m0, s54
	s_nop 0
	global_load_lds_dwordx4 v[238:239], off
	s_waitcnt vmcnt(8)
	s_waitcnt lgkmcnt(0)
	s_barrier
	s_setprio 1
	v_mfma_f32_16x16x32_bf16 v[126:129], v[140:143], v[198:201], v[126:129]
	v_mfma_f32_16x16x32_bf16 v[122:125], v[154:157], v[198:201], v[122:125]
	v_mfma_f32_16x16x32_bf16 v[110:113], v[140:143], v[206:209], v[110:113]
	v_mfma_f32_16x16x32_bf16 v[106:109], v[154:157], v[206:209], v[106:109]
	v_mfma_f32_16x16x32_bf16 v[94:97], v[140:143], v[214:217], v[94:97]
	v_mfma_f32_16x16x32_bf16 v[90:93], v[154:157], v[214:217], v[90:93]
	v_mfma_f32_16x16x32_bf16 v[78:81], v[140:143], v[222:225], v[78:81]
	v_mfma_f32_16x16x32_bf16 v[74:77], v[154:157], v[222:225], v[74:77]
	v_mfma_f32_16x16x32_bf16 v[126:129], v[150:153], v[202:205], v[126:129]
	v_mfma_f32_16x16x32_bf16 v[122:125], v[158:161], v[202:205], v[122:125]
	v_mfma_f32_16x16x32_bf16 v[110:113], v[150:153], v[210:213], v[110:113]
	v_mfma_f32_16x16x32_bf16 v[106:109], v[158:161], v[210:213], v[106:109]
	v_mfma_f32_16x16x32_bf16 v[94:97], v[150:153], v[218:221], v[94:97]
	v_mfma_f32_16x16x32_bf16 v[90:93], v[158:161], v[218:221], v[90:93]
	v_mfma_f32_16x16x32_bf16 v[78:81], v[150:153], v[226:229], v[78:81]
	v_mfma_f32_16x16x32_bf16 v[74:77], v[158:161], v[226:229], v[74:77]
	v_mfma_f32_16x16x32_bf16 v[118:121], v[176:179], v[198:201], v[118:121]
	v_mfma_f32_16x16x32_bf16 v[114:117], v[190:193], v[198:201], v[114:117]
	v_mfma_f32_16x16x32_bf16 v[102:105], v[176:179], v[206:209], v[102:105]
	v_mfma_f32_16x16x32_bf16 v[98:101], v[190:193], v[206:209], v[98:101]
	v_mfma_f32_16x16x32_bf16 v[86:89], v[176:179], v[214:217], v[86:89]
	v_mfma_f32_16x16x32_bf16 v[82:85], v[190:193], v[214:217], v[82:85]
	v_mfma_f32_16x16x32_bf16 v[70:73], v[176:179], v[222:225], v[70:73]
	v_mfma_f32_16x16x32_bf16 v[66:69], v[190:193], v[222:225], v[66:69]
	v_mfma_f32_16x16x32_bf16 v[118:121], v[180:183], v[202:205], v[118:121]
	v_mfma_f32_16x16x32_bf16 v[114:117], v[194:197], v[202:205], v[114:117]
	v_mfma_f32_16x16x32_bf16 v[102:105], v[180:183], v[210:213], v[102:105]
	v_mfma_f32_16x16x32_bf16 v[98:101], v[194:197], v[210:213], v[98:101]
	v_mfma_f32_16x16x32_bf16 v[86:89], v[180:183], v[218:221], v[86:89]
	v_mfma_f32_16x16x32_bf16 v[82:85], v[194:197], v[218:221], v[82:85]
	v_mfma_f32_16x16x32_bf16 v[70:73], v[180:183], v[226:229], v[70:73]
	v_mfma_f32_16x16x32_bf16 v[66:69], v[194:197], v[226:229], v[66:69]
	s_setprio 0
	s_barrier
; #define PG8_STAGE(bufoff, gbase, voff) do { _Pragma("unroll") for (int _i = 0; _i < 2; ++_i) \
;         __builtin_amdgcn_global_load_lds((const unsigned*)((const char*)(gbase) + (voff)[_i]), (LAS unsigned*)(lds + (bufoff) + ldsw + _i * 8192), 16, 0, 0); } while (0)
; #define PG8_LDA(dst, b, h) do { _Pragma("unroll") for (int m = 0; m < 4; ++m) _Pragma("unroll") for (int k = 0; k < 2; ++k) dst[m][k] = *(const LAS bf16x8*)(lds + PG8_SA(b, h) + aoff + m * 2048 + k * 1024); } while (0)
; #define PG8_MMA(ai, bj, At, Bt) do { __builtin_amdgcn_s_setprio(1); _Pragma("unroll") for (int m = 0; m < 4; ++m) _Pragma("unroll") for (int n = 0; n < 2; ++n) _Pragma("unroll") for (int k = 0; k < 2; ++k) \
;         acc[ai][bj][m][n] = __builtin_amdgcn_mfma_f32_16x16x32_bf16(Bt[n][k], At[m][k], acc[ai][bj][m][n], 0, 0, 0); __builtin_amdgcn_s_setprio(0); } while (0)
; #define PG8_WAIT_V(n) asm volatile("s_waitcnt vmcnt(" #n ")" ::: "memory")
; #define PG8_WAIT_L(n) asm volatile("s_waitcnt lgkmcnt(" #n ")" ::: "memory")
; #define PG8_BAR __builtin_amdgcn_s_barrier()
; #define PG8_SCHED __builtin_amdgcn_sched_barrier(0)
; template <class Epi>
; DI void gemm_phase(int wid0, LAS unsigned char* lds, const Gemm g, const StaticOrder& S, const Epi& E) {
;     ...
;             PG8_LDA(At, 1, 1); PG8_STAGE(PG8_SB(1, 0), b3, voffB); PG8_STAGE(PG8_SB(1, 1), b3 + hstep, voffB); PG8_STAGE(PG8_SA(1, 0), a3, voffA);
;             PG8_WAIT_V(8); PG8_WAIT_L(0); PG8_BAR; PG8_MMA(1, 0, At, B0); PG8_MMA(1, 1, At, B1); PG8_BAR; PG8_SCHED;
;         }
;         if (wr == 0) PG8_BAR;
	s_add_i32 s48, s72, s40
	v_lshl_add_u64 v[144:145], v[144:145], 0, s[30:31]
	s_mov_b32 m0, s48
	ds_read_b128 v[198:201], v149 offset:49152
	ds_read_b128 v[202:205], v149 offset:50176
	ds_read_b128 v[206:209], v149 offset:51200
	ds_read_b128 v[210:213], v149 offset:52224
	ds_read_b128 v[214:217], v149 offset:53248
	ds_read_b128 v[218:221], v149 offset:54272
	ds_read_b128 v[222:225], v149 offset:55296
	ds_read_b128 v[226:229], v149 offset:56320
	global_load_lds_dwordx4 v[144:145], off
	s_add_i32 m0, s48, 0x2000
	s_add_u32 s46, s46, 0x80080
	v_lshl_add_u64 v[144:145], v[162:163], 0, s[30:31]
	s_addc_u32 s47, s47, 0
	s_add_i32 s48, s73, s40
	global_load_lds_dwordx4 v[144:145], off
	v_lshl_add_u64 v[144:145], s[46:47], 0, v[0:1]
	s_mov_b32 m0, s48
	s_nop 0
	global_load_lds_dwordx4 v[144:145], off
	s_add_i32 m0, s48, 0x2000
	s_nop 0
	global_load_lds_dwordx4 v130, s[46:47]
	v_lshl_add_u64 v[144:145], v[230:231], 0, s[30:31]
	s_mov_b32 m0, s2
	s_nop 0
	global_load_lds_dwordx4 v[144:145], off
	v_lshl_add_u64 v[144:145], v[236:237], 0, s[30:31]
	s_mov_b32 m0, s55
	s_nop 0
	global_load_lds_dwordx4 v[144:145], off
	s_waitcnt vmcnt(8)
	s_waitcnt lgkmcnt(0)
	s_barrier
	s_setprio 1
	v_mfma_f32_16x16x32_bf16 v[62:65], v[140:143], v[198:201], v[62:65]
	v_mfma_f32_16x16x32_bf16 v[58:61], v[154:157], v[198:201], v[58:61]
	v_mfma_f32_16x16x32_bf16 v[46:49], v[140:143], v[206:209], v[46:49]
	v_mfma_f32_16x16x32_bf16 v[42:45], v[154:157], v[206:209], v[42:45]
	v_mfma_f32_16x16x32_bf16 v[30:33], v[140:143], v[214:217], v[30:33]
	v_mfma_f32_16x16x32_bf16 v[26:29], v[154:157], v[214:217], v[26:29]
	v_mfma_f32_16x16x32_bf16 v[14:17], v[140:143], v[222:225], v[14:17]
	v_mfma_f32_16x16x32_bf16 v[10:13], v[154:157], v[222:225], v[10:13]
	v_mfma_f32_16x16x32_bf16 v[62:65], v[150:153], v[202:205], v[62:65]
	v_mfma_f32_16x16x32_bf16 v[58:61], v[158:161], v[202:205], v[58:61]
	v_mfma_f32_16x16x32_bf16 v[46:49], v[150:153], v[210:213], v[46:49]
	v_mfma_f32_16x16x32_bf16 v[42:45], v[158:161], v[210:213], v[42:45]
	v_mfma_f32_16x16x32_bf16 v[30:33], v[150:153], v[218:221], v[30:33]
	v_mfma_f32_16x16x32_bf16 v[26:29], v[158:161], v[218:221], v[26:29]
	v_mfma_f32_16x16x32_bf16 v[14:17], v[150:153], v[226:229], v[14:17]
	v_mfma_f32_16x16x32_bf16 v[10:13], v[158:161], v[226:229], v[10:13]
	v_mfma_f32_16x16x32_bf16 v[54:57], v[176:179], v[198:201], v[54:57]
	v_mfma_f32_16x16x32_bf16 v[50:53], v[190:193], v[198:201], v[50:53]
	v_mfma_f32_16x16x32_bf16 v[38:41], v[176:179], v[206:209], v[38:41]
	v_mfma_f32_16x16x32_bf16 v[34:37], v[190:193], v[206:209], v[34:37]
	v_mfma_f32_16x16x32_bf16 v[22:25], v[176:179], v[214:217], v[22:25]
	v_mfma_f32_16x16x32_bf16 v[18:21], v[190:193], v[214:217], v[18:21]
	v_mfma_f32_16x16x32_bf16 v[6:9], v[176:179], v[222:225], v[6:9]
	v_mfma_f32_16x16x32_bf16 v[2:5], v[190:193], v[222:225], v[2:5]
	v_mfma_f32_16x16x32_bf16 v[54:57], v[180:183], v[202:205], v[54:57]
	v_mfma_f32_16x16x32_bf16 v[50:53], v[194:197], v[202:205], v[50:53]
	v_mfma_f32_16x16x32_bf16 v[38:41], v[180:183], v[210:213], v[38:41]
	v_mfma_f32_16x16x32_bf16 v[34:37], v[194:197], v[210:213], v[34:37]
	v_mfma_f32_16x16x32_bf16 v[22:25], v[180:183], v[218:221], v[22:25]
	v_mfma_f32_16x16x32_bf16 v[18:21], v[194:197], v[218:221], v[18:21]
	v_mfma_f32_16x16x32_bf16 v[6:9], v[180:183], v[226:229], v[6:9]
	v_mfma_f32_16x16x32_bf16 v[2:5], v[194:197], v[226:229], v[2:5]
	s_setprio 0
	s_barrier
	s_add_i32 s71, s71, 2
	s_add_u32 s44, s44, 0x100
	s_addc_u32 s45, s45, 0
	s_add_u32 s69, s69, 0x100
	s_addc_u32 s70, s70, 0
	s_cmp_gt_u32 s71, 29
	s_cbranch_scc0 .LBB0_207
	s_and_b64 vcc, exec, s[14:15]
	s_cbranch_vccz .LBB0_210
	s_barrier

; DI void phase_scan(int wid0, const Params& p, unsigned char* lds, bool dry) {
;     ...
;             const unsigned vao = vs_base + (unsigned)(cur * 9216 + (8 * l4 + (l15 >> 2)) * 144 + 2 * (16 * cb0 + 4 * (l15 & 3)));
;             const unsigned vau = vs_base + (unsigned)(cur * 9216 + (8 * hi + (l15 >> 2)) * 144 + 2 * (16 * ((lane >> 4) & 1) + 4 * (l15 & 3)));
;             s16x4 ol[2][2], oh[2][2], ul0[4], uh0[4], ul1[4], uh1[4];
; #pragma unroll
;             for (int cc = 0; cc < 2; ++cc)
; #pragma unroll
;                 for (int s = 0; s < 2; ++s) { ol[cc][s] = tr_read0(vao + cc * 32 + s * 32 * 144); oh[cc][s] = tr_read0(vao + cc * 32 + s * 32 * 144 + 4 * 144); }
; #pragma unroll
;             for (int s = 0; s < 2; ++s) {
;                 ul0[s] = tr_read0(vau + s * 16 * 144); uh0[s] = tr_read0(vau + s * 16 * 144 + 4 * 144);
;                 ul1[s] = tr_read0(vau + s * 16 * 144 + 64); uh1[s] = tr_read0(vau + s * 16 * 144 + 4 * 144 + 64);
;             }
;             {
;                 __builtin_amdgcn_sched_barrier(0);
;                 f32x4 oacc[2];
; #pragma unroll
;                 for (int cc = 0; cc < 2; ++cc) {
;                     const int cb = cb0 + cc; oacc[cc] = (f32x4){0.f, 0.f, 0.f, 0.f};
; #pragma unroll
;                     for (int s = 0; s < 2; ++s) oacc[cc] = MFMA16(PK8(ol[cc][s], oh[cc][s]), at[s], oacc[cc]);
;                     const bf16_t* sp = sbt + cur * 16896 + (16 * cb + l15) * 264 + 8 * l4;
; #pragma unroll
;                     for (int s = 0; s < 8; ++s) { const bf16x8 bfr = *(const bf16x8*)(sp + 32 * s); oacc[cc] = MFMA16(bfr, aq[s], oacc[cc]); }
;                 }
; #pragma unroll
;                 for (int s = 2; s < 4; ++s) {
;                     ul0[s] = tr_read0(vau + s * 16 * 144); uh0[s] = tr_read0(vau + s * 16 * 144 + 4 * 144);
;                     ul1[s] = tr_read0(vau + s * 16 * 144 + 64); uh1[s] = tr_read0(vau + s * 16 * 144 + 4 * 144 + 64);
;                 }
; #pragma unroll
;                 for (int cc = 0; cc < 2; ++cc) {
;                     const int col = colv + 16 * (cb0 + cc) + 4 * l4;
;                     u32x2 w; w.x = cvt_pk_bf16(oacc[cc][0], oacc[cc][1]); w.y = cvt_pk_bf16(oacc[cc][2], oacc[cc][3]);
;                     if (dry) {} else if (c > 0) *(u32x2*)(vb + (size_t)(row0 + i) * 2048 + col) = w;
.LBB0_239:
	v_add_u32_e32 v62, s9, v181
	v_add_u32_e32 v179, s9, v180
	ds_read_b64_tr_b16 v[198:199], v62 offset:576
	ds_read_b64_tr_b16 v[196:197], v62
	ds_read_b64_tr_b16 v[202:203], v62 offset:608
	ds_read_b64_tr_b16 v[200:201], v62 offset:32
	ds_read_b64_tr_b16 v[204:205], v62 offset:4608
	ds_read_b64_tr_b16 v[206:207], v62 offset:5184
	ds_read_b64_tr_b16 v[210:211], v62 offset:5216
	ds_read_b64_tr_b16 v[208:209], v62 offset:4640
	ds_read_b64_tr_b16 v[82:83], v179
	ds_read_b64_tr_b16 v[84:85], v179 offset:576
	ds_read_b64_tr_b16 v[80:81], v179 offset:640
	ds_read_b64_tr_b16 v[78:79], v179 offset:64
	ds_read_b64_tr_b16 v[74:75], v179 offset:2304
	ds_read_b64_tr_b16 v[76:77], v179 offset:2880
	ds_read_b64_tr_b16 v[64:65], v179 offset:2944
	ds_read_b64_tr_b16 v[62:63], v179 offset:2368
	s_waitcnt vmcnt(17) lgkmcnt(14)
	v_mfma_f32_16x16x32_bf16 v[196:199], v[196:199], v[118:121], 0
	s_mul_i32 s9, s7, 0x8400
	v_add_u32_e32 v212, s9, v182
	v_add_u32_e32 v213, v212, v145
	s_waitcnt lgkmcnt(12)
	v_mfma_f32_16x16x32_bf16 v[118:121], v[200:203], v[118:121], 0
	v_add_u32_e32 v200, v212, v189
	s_waitcnt vmcnt(0)
	v_pk_mul_f32 v[32:33], v[32:33], v[72:73]
	v_pk_mul_f32 v[28:29], v[28:29], v[60:61]
	s_waitcnt lgkmcnt(10)
	v_mfma_f32_16x16x32_bf16 v[196:199], v[204:207], v[122:125], v[196:199]
	ds_read_b128 v[214:217], v213
	v_pk_mul_f32 v[24:25], v[24:25], v[56:57]
	v_pk_mul_f32 v[20:21], v[20:21], v[68:69]
	s_waitcnt lgkmcnt(9)
	v_mfma_f32_16x16x32_bf16 v[118:121], v[208:211], v[122:125], v[118:121]
	ds_read_b128 v[218:221], v200
	v_pk_mul_f32 v[18:19], v[18:19], v[66:67]
	v_pk_mul_f32 v[30:31], v[30:31], v[70:71]
	ds_read_b128 v[222:225], v213 offset:64
	ds_read_b128 v[226:229], v200 offset:64
	s_waitcnt lgkmcnt(3)
	v_mfma_f32_16x16x32_bf16 v[196:199], v[214:217], v[114:117], v[196:199]
	v_pk_mul_f32 v[26:27], v[26:27], v[58:59]
	v_pk_mul_f32 v[22:23], v[22:23], v[54:55]
	ds_read_b128 v[236:239], v213 offset:128
	s_waitcnt lgkmcnt(3)
	v_mfma_f32_16x16x32_bf16 v[114:117], v[218:221], v[114:117], v[118:121]
	v_mul_f32_e64 v16, v16, v72
	v_mul_f32_e64 v17, v17, v73
	v_pk_mul_f32 v[12:13], v[12:13], v[60:61]
	v_pk_mul_f32 v[8:9], v[8:9], v[56:57]
	ds_read_b128 v[240:243], v200 offset:128
	s_waitcnt lgkmcnt(3)
	v_mfma_f32_16x16x32_bf16 v[196:199], v[222:225], v[98:101], v[196:199]
	v_pk_mul_f32 v[4:5], v[4:5], v[68:69]
	v_pk_mul_f32 v[2:3], v[2:3], v[66:67]
	ds_read_b128 v[248:251], v213 offset:192
	s_waitcnt lgkmcnt(3)
	v_mfma_f32_16x16x32_bf16 v[98:101], v[226:229], v[98:101], v[114:117]
	v_pk_mul_f32 v[14:15], v[14:15], v[70:71]
	v_pk_mul_f32 v[10:11], v[10:11], v[58:59]
	ds_read_b128 v[252:255], v200 offset:192
	s_waitcnt lgkmcnt(3)
	v_mfma_f32_16x16x32_bf16 v[196:199], v[236:239], v[110:113], v[196:199]
	v_pk_mul_f32 v[6:7], v[6:7], v[54:55]
	ds_read_b128 v[214:217], v213 offset:256
	s_waitcnt lgkmcnt(3)
	v_mfma_f32_16x16x32_bf16 v[98:101], v[240:243], v[110:113], v[98:101]
	ds_read_b128 v[218:221], v200 offset:256
	s_waitcnt lgkmcnt(3)
	v_mfma_f32_16x16x32_bf16 v[196:199], v[248:251], v[86:89], v[196:199]
	ds_read_b128 v[222:225], v213 offset:320
	s_waitcnt lgkmcnt(3)
	v_mfma_f32_16x16x32_bf16 v[86:89], v[252:255], v[86:89], v[98:101]
	ds_read_b128 v[226:229], v200 offset:320
	s_waitcnt lgkmcnt(3)
	v_mfma_f32_16x16x32_bf16 v[196:199], v[214:217], v[102:105], v[196:199]
	ds_read_b128 v[236:239], v213 offset:384
	s_waitcnt lgkmcnt(3)
	v_mfma_f32_16x16x32_bf16 v[86:89], v[218:221], v[102:105], v[86:89]
	ds_read_b128 v[240:243], v200 offset:384
	s_waitcnt lgkmcnt(3)
	v_mfma_f32_16x16x32_bf16 v[196:199], v[222:225], v[90:93], v[196:199]
	ds_read_b128 v[248:251], v213 offset:448
	s_waitcnt lgkmcnt(3)
	v_mfma_f32_16x16x32_bf16 v[86:89], v[226:229], v[90:93], v[86:89]
	ds_read_b128 v[252:255], v200 offset:448
	s_waitcnt lgkmcnt(3)
	v_mfma_f32_16x16x32_bf16 v[196:199], v[236:239], v[106:109], v[196:199]
	s_waitcnt lgkmcnt(2)
	v_mfma_f32_16x16x32_bf16 v[86:89], v[240:243], v[106:109], v[86:89]
	v_add_u32_e32 v106, s8, v194
	v_ashrrev_i32_e32 v107, 31, v106
	s_waitcnt lgkmcnt(1)
	v_mfma_f32_16x16x32_bf16 v[196:199], v[248:251], v[94:97], v[196:199]
	v_lshlrev_b64 v[106:107], 12, v[106:107]
	v_lshl_add_u64 v[106:107], s[28:29], 0, v[106:107]
	v_lshl_add_u64 v[110:111], v[106:107], 0, v[0:1]
	s_waitcnt lgkmcnt(0)
	v_mfma_f32_16x16x32_bf16 v[86:89], v[252:255], v[94:97], v[86:89]
	ds_read_b64_tr_b16 v[90:91], v179 offset:4608
	ds_read_b64_tr_b16 v[92:93], v179 offset:5184
	ds_read_b64_tr_b16 v[94:95], v179 offset:4672
	ds_read_b64_tr_b16 v[96:97], v179 offset:5248
	ds_read_b64_tr_b16 v[98:99], v179 offset:6912
	ds_read_b64_tr_b16 v[100:101], v179 offset:7488
	ds_read_b64_tr_b16 v[102:103], v179 offset:6976
	ds_read_b64_tr_b16 v[104:105], v179 offset:7552
	v_mov_b32_e32 v179, v1
	v_cvt_pk_bf16_f32 v108, v196, v197
	v_cvt_pk_bf16_f32 v109, v198, v199
	v_cvt_pk_bf16_f32 v86, v86, v87
	v_cvt_pk_bf16_f32 v87, v88, v89
	v_lshl_add_u64 v[88:89], v[106:107], 0, v[178:179]
	global_store_dwordx2 v[110:111], v[108:109], off
	global_store_dwordx2 v[88:89], v[86:87], off
	v_mfma_f32_32x32x16_bf16 v[18:33], v[50:53], v[82:85], v[18:33]
	s_xor_b32 s7, s7, 1
	s_mul_i32 s7, s7, 0x8400
	s_add_i32 s8, s8, 64
	s_add_i32 s6, s6, 4
	s_add_i32 s2, s2, 1
	s_cmpk_eq_i32 s8, 0x1000
	v_mfma_f32_32x32x16_bf16 v[2:17], v[50:53], v[78:81], v[2:17]
	v_mfma_f32_32x32x16_bf16 v[18:33], v[46:49], v[74:77], v[18:33]
	v_mfma_f32_32x32x16_bf16 v[2:17], v[46:49], v[62:65], v[2:17]
	v_add_u32_e32 v46, s7, v131
	v_add_u32_e32 v47, 0x4000, v46
	s_waitcnt lgkmcnt(6)
	v_mfma_f32_32x32x16_bf16 v[18:33], v[42:45], v[90:93], v[18:33]
	s_waitcnt lgkmcnt(4)
	v_mfma_f32_32x32x16_bf16 v[2:17], v[42:45], v[94:97], v[2:17]
	s_waitcnt lgkmcnt(2)
	v_mfma_f32_32x32x16_bf16 v[18:33], v[38:41], v[98:101], v[18:33]
	s_waitcnt lgkmcnt(0)
	v_mfma_f32_32x32x16_bf16 v[2:17], v[38:41], v[102:105], v[2:17]
	s_nop 9
	v_cvt_pk_bf16_f32 v42, v18, v19
	v_cvt_pk_bf16_f32 v43, v20, v21
	v_cvt_pk_bf16_f32 v40, v22, v23
	v_cvt_pk_bf16_f32 v41, v24, v25
	ds_write2_b64 v46, v[42:43], v[40:41] offset1:2
	v_cvt_pk_bf16_f32 v42, v30, v31
	v_cvt_pk_bf16_f32 v43, v32, v33
	v_cvt_pk_bf16_f32 v38, v2, v3
	v_cvt_pk_bf16_f32 v39, v4, v5
	v_cvt_pk_bf16_f32 v44, v6, v7
	v_cvt_pk_bf16_f32 v45, v8, v9
	ds_write2_b64 v47, v[38:39], v[44:45] offset0:64 offset1:66
	v_cvt_pk_bf16_f32 v38, v26, v27
	v_cvt_pk_bf16_f32 v39, v28, v29
	v_cvt_pk_bf16_f32 v40, v10, v11
	v_cvt_pk_bf16_f32 v41, v12, v13
	v_cvt_pk_bf16_f32 v44, v14, v15
	v_cvt_pk_bf16_f32 v45, v16, v17
	ds_write2_b64 v46, v[38:39], v[42:43] offset0:4 offset1:6
	ds_write2_b64 v47, v[40:41], v[44:45] offset0:68 offset1:70
	s_cbranch_scc1 .LBB0_228

; #define PG8_STAGE(bufoff, gbase, voff) do { _Pragma("unroll") for (int _i = 0; _i < 2; ++_i) \
;         __builtin_amdgcn_global_load_lds((const unsigned*)((const char*)(gbase) + (voff)[_i]), (LAS unsigned*)(lds + (bufoff) + ldsw + _i * 8192), 16, 0, 0); } while (0)
; #define PG8_LDA(dst, b, h) do { _Pragma("unroll") for (int m = 0; m < 4; ++m) _Pragma("unroll") for (int k = 0; k < 2; ++k) dst[m][k] = *(const LAS bf16x8*)(lds + PG8_SA(b, h) + aoff + m * 2048 + k * 1024); } while (0)
; #define PG8_LDB(dst, b, h) do { _Pragma("unroll") for (int n = 0; n < 2; ++n) _Pragma("unroll") for (int k = 0; k < 2; ++k) dst[n][k] = *(const LAS bf16x8*)(lds + PG8_SB(b, h) + boff + n * 2048 + k * 1024); } while (0)
; #define PG8_MMA(ai, bj, At, Bt) do { __builtin_amdgcn_s_setprio(1); _Pragma("unroll") for (int m = 0; m < 4; ++m) _Pragma("unroll") for (int n = 0; n < 2; ++n) _Pragma("unroll") for (int k = 0; k < 2; ++k) \
;         acc[ai][bj][m][n] = __builtin_amdgcn_mfma_f32_16x16x32_bf16(Bt[n][k], At[m][k], acc[ai][bj][m][n], 0, 0, 0); __builtin_amdgcn_s_setprio(0); } while (0)
; #define PG8_WAIT_V(n) asm volatile("s_waitcnt vmcnt(" #n ")" ::: "memory")
; #define PG8_BAR __builtin_amdgcn_s_barrier()
; template <class Epi>
; DI void gemm_phase(int wid0, LAS unsigned char* lds, const Gemm g, const StaticOrder& S, const Epi& E) {
;     ...
;         const char* nA = has_next ? (const char*)g.A + (size_t)nxt.pm * tstep : cA; const char* nB = has_next ? (const char*)g.Bt + (size_t)nxt.pn * tstep : cB;
;         for (int t = 0; t < nt; t += 2) {
;             const bool last = (t == nt - 2);
;             const char* a1 = cA + (size_t)(t + 1) * kstep;
;             const char* a2 = last ? nA : cA + (size_t)(t + 2) * kstep; const char* b2 = last ? nB : cB + (size_t)(t + 2) * kstep;
;             const char* a3 = a2 + kstep; const char* b3 = b2 + kstep;
;             PG8_LDB(B0, 0, 0); PG8_LDB(B1, 0, 1); PG8_SCHED; PG8_LDA(At, 0, 0); PG8_STAGE(PG8_SA(1, 1), a1 + hstep, voffA);
;             PG8_WAIT_V(8); PG8_WAIT_L(0); PG8_BAR; PG8_MMA(0, 0, At, B0); PG8_MMA(0, 1, At, B1); PG8_BAR; PG8_SCHED;
;             PG8_LDA(At, 0, 1); PG8_STAGE(PG8_SB(0, 0), b2, voffB); PG8_STAGE(PG8_SB(0, 1), b2 + hstep, voffB); PG8_STAGE(PG8_SA(0, 0), a2, voffA);
;             PG8_WAIT_V(8); PG8_WAIT_L(0); PG8_BAR; PG8_MMA(1, 0, At, B0); PG8_MMA(1, 1, At, B1); PG8_BAR; PG8_SCHED;
.LBB0_277:
	s_add_u32 s38, s28, 0xfffc0080
	s_addc_u32 s39, s29, -1
	s_add_i32 s54, 0, 0x10000
	s_cmp_eq_u32 s51, 12
	s_cselect_b32 s41, s7, s39
	s_cselect_b32 s40, s9, s38
	v_add_u32_e32 v0, s54, v153
	s_cselect_b32 s39, s10, s19
	s_cselect_b32 s38, s11, s17
	s_add_i32 s56, 0, 0x14000
	ds_read_b128 v[142:145], v0
	ds_read_b128 v[146:149], v0 offset:1024
	ds_read_b128 v[156:159], v0 offset:2048
	ds_read_b128 v[160:163], v0 offset:3072
	v_add_u32_e32 v0, s56, v153
	ds_read_b128 v[176:179], v0
	ds_read_b128 v[180:183], v0 offset:1024
	ds_read_b128 v[190:193], v0 offset:2048
	ds_read_b128 v[194:197], v0 offset:3072
	s_add_i32 m0, s44, 0xc000
	ds_read_b128 v[198:201], v155
	ds_read_b128 v[202:205], v155 offset:1024
	ds_read_b128 v[206:209], v155 offset:2048
	ds_read_b128 v[210:213], v155 offset:3072
	ds_read_b128 v[214:217], v155 offset:4096
	ds_read_b128 v[218:221], v155 offset:5120
	ds_read_b128 v[222:225], v155 offset:6144
	ds_read_b128 v[226:229], v155 offset:7168
	global_load_lds_dwordx4 v138, s[28:29]
	s_add_i32 m0, s44, 0xe000
	s_nop 0
	global_load_lds_dwordx4 v140, s[28:29]
	s_waitcnt vmcnt(8)
	s_waitcnt lgkmcnt(0)
	s_barrier
	s_setprio 1
	v_mfma_f32_16x16x32_bf16 v[126:129], v[142:145], v[198:201], v[126:129]
	v_mfma_f32_16x16x32_bf16 v[122:125], v[156:159], v[198:201], v[122:125]
	v_mfma_f32_16x16x32_bf16 v[110:113], v[142:145], v[206:209], v[110:113]
	v_mfma_f32_16x16x32_bf16 v[106:109], v[156:159], v[206:209], v[106:109]
	v_mfma_f32_16x16x32_bf16 v[94:97], v[142:145], v[214:217], v[94:97]
	v_mfma_f32_16x16x32_bf16 v[90:93], v[156:159], v[214:217], v[90:93]
	v_mfma_f32_16x16x32_bf16 v[78:81], v[142:145], v[222:225], v[78:81]
	v_mfma_f32_16x16x32_bf16 v[74:77], v[156:159], v[222:225], v[74:77]
	v_mfma_f32_16x16x32_bf16 v[126:129], v[146:149], v[202:205], v[126:129]
	v_mfma_f32_16x16x32_bf16 v[122:125], v[160:163], v[202:205], v[122:125]
	v_mfma_f32_16x16x32_bf16 v[110:113], v[146:149], v[210:213], v[110:113]
	v_mfma_f32_16x16x32_bf16 v[106:109], v[160:163], v[210:213], v[106:109]
	v_mfma_f32_16x16x32_bf16 v[94:97], v[146:149], v[218:221], v[94:97]
	v_mfma_f32_16x16x32_bf16 v[90:93], v[160:163], v[218:221], v[90:93]
	v_mfma_f32_16x16x32_bf16 v[78:81], v[146:149], v[226:229], v[78:81]
	v_mfma_f32_16x16x32_bf16 v[74:77], v[160:163], v[226:229], v[74:77]
	v_mfma_f32_16x16x32_bf16 v[118:121], v[176:179], v[198:201], v[118:121]
	v_mfma_f32_16x16x32_bf16 v[114:117], v[190:193], v[198:201], v[114:117]
	v_mfma_f32_16x16x32_bf16 v[102:105], v[176:179], v[206:209], v[102:105]
	v_mfma_f32_16x16x32_bf16 v[98:101], v[190:193], v[206:209], v[98:101]
	v_mfma_f32_16x16x32_bf16 v[86:89], v[176:179], v[214:217], v[86:89]
	v_mfma_f32_16x16x32_bf16 v[82:85], v[190:193], v[214:217], v[82:85]
	v_mfma_f32_16x16x32_bf16 v[70:73], v[176:179], v[222:225], v[70:73]
	v_mfma_f32_16x16x32_bf16 v[66:69], v[190:193], v[222:225], v[66:69]
	v_mfma_f32_16x16x32_bf16 v[118:121], v[180:183], v[202:205], v[118:121]
	v_mfma_f32_16x16x32_bf16 v[114:117], v[194:197], v[202:205], v[114:117]
	v_mfma_f32_16x16x32_bf16 v[102:105], v[180:183], v[210:213], v[102:105]
	v_mfma_f32_16x16x32_bf16 v[98:101], v[194:197], v[210:213], v[98:101]
	v_mfma_f32_16x16x32_bf16 v[86:89], v[180:183], v[218:221], v[86:89]
	v_mfma_f32_16x16x32_bf16 v[82:85], v[194:197], v[218:221], v[82:85]
	v_mfma_f32_16x16x32_bf16 v[70:73], v[180:183], v[226:229], v[70:73]
	v_mfma_f32_16x16x32_bf16 v[66:69], v[194:197], v[226:229], v[66:69]
	s_setprio 0
	s_barrier
	s_add_i32 s54, s54, s2
	v_lshl_add_u64 v[150:151], s[38:39], 0, v[132:133]
	s_mov_b32 m0, s54
	ds_read_b128 v[198:201], v155 offset:16384
	ds_read_b128 v[202:205], v155 offset:17408
	ds_read_b128 v[206:209], v155 offset:18432
	ds_read_b128 v[210:213], v155 offset:19456
	ds_read_b128 v[214:217], v155 offset:20480
	ds_read_b128 v[218:221], v155 offset:21504
	ds_read_b128 v[222:225], v155 offset:22528
	ds_read_b128 v[226:229], v155 offset:23552
	global_load_lds_dwordx4 v[150:151], off
	s_add_i32 m0, s54, 0x2000
	s_add_u32 s54, s38, 0x40000
	v_lshl_add_u64 v[230:231], s[38:39], 0, v[136:137]
	s_addc_u32 s55, s39, 0
	s_add_i32 s56, s56, s2
	global_load_lds_dwordx4 v[230:231], off
	s_mov_b32 m0, s56
	v_lshl_add_u64 v[238:239], s[40:41], 0, v[134:135]
	global_load_lds_dwordx4 v132, s[54:55]
	s_add_i32 m0, s56, 0x2000
	s_nop 0
	global_load_lds_dwordx4 v136, s[54:55]
	v_lshl_add_u64 v[236:237], s[40:41], 0, v[130:131]
	s_mov_b32 m0, s44
	s_nop 0
	global_load_lds_dwordx4 v[236:237], off
	s_mov_b32 m0, s45
	s_nop 0
	global_load_lds_dwordx4 v[238:239], off
	s_waitcnt vmcnt(8)
	s_waitcnt lgkmcnt(0)
	s_barrier
; #define PG8_STAGE(bufoff, gbase, voff) do { _Pragma("unroll") for (int _i = 0; _i < 2; ++_i) \
;         __builtin_amdgcn_global_load_lds((const unsigned*)((const char*)(gbase) + (voff)[_i]), (LAS unsigned*)(lds + (bufoff) + ldsw + _i * 8192), 16, 0, 0); } while (0)
; #define PG8_LDA(dst, b, h) do { _Pragma("unroll") for (int m = 0; m < 4; ++m) _Pragma("unroll") for (int k = 0; k < 2; ++k) dst[m][k] = *(const LAS bf16x8*)(lds + PG8_SA(b, h) + aoff + m * 2048 + k * 1024); } while (0)
; #define PG8_LDB(dst, b, h) do { _Pragma("unroll") for (int n = 0; n < 2; ++n) _Pragma("unroll") for (int k = 0; k < 2; ++k) dst[n][k] = *(const LAS bf16x8*)(lds + PG8_SB(b, h) + boff + n * 2048 + k * 1024); } while (0)
; #define PG8_MMA(ai, bj, At, Bt) do { __builtin_amdgcn_s_setprio(1); _Pragma("unroll") for (int m = 0; m < 4; ++m) _Pragma("unroll") for (int n = 0; n < 2; ++n) _Pragma("unroll") for (int k = 0; k < 2; ++k) \
;         acc[ai][bj][m][n] = __builtin_amdgcn_mfma_f32_16x16x32_bf16(Bt[n][k], At[m][k], acc[ai][bj][m][n], 0, 0, 0); __builtin_amdgcn_s_setprio(0); } while (0)
; #define PG8_WAIT_V(n) asm volatile("s_waitcnt vmcnt(" #n ")" ::: "memory")
; #define PG8_WAIT_L(n) asm volatile("s_waitcnt lgkmcnt(" #n ")" ::: "memory")
; #define PG8_BAR __builtin_amdgcn_s_barrier()
; #define PG8_SCHED __builtin_amdgcn_sched_barrier(0)
; template <class Epi>
; DI void gemm_phase(int wid0, LAS unsigned char* lds, const Gemm g, const StaticOrder& S, const Epi& E) {
;     ...
;             PG8_WAIT_V(8); PG8_WAIT_L(0); PG8_BAR; PG8_MMA(1, 0, At, B0); PG8_MMA(1, 1, At, B1); PG8_BAR; PG8_SCHED;
;             PG8_LDB(B0, 1, 0); PG8_LDB(B1, 1, 1); PG8_SCHED; PG8_LDA(At, 1, 0); PG8_STAGE(PG8_SA(0, 1), a2 + hstep, voffA);
;             PG8_WAIT_V(8); PG8_WAIT_L(0); PG8_BAR; PG8_MMA(0, 0, At, B0); PG8_MMA(0, 1, At, B1); PG8_BAR; PG8_SCHED;
	s_setprio 1
	v_mfma_f32_16x16x32_bf16 v[62:65], v[142:145], v[198:201], v[62:65]
	v_mfma_f32_16x16x32_bf16 v[58:61], v[156:159], v[198:201], v[58:61]
	v_mfma_f32_16x16x32_bf16 v[46:49], v[142:145], v[206:209], v[46:49]
	v_mfma_f32_16x16x32_bf16 v[42:45], v[156:159], v[206:209], v[42:45]
	v_mfma_f32_16x16x32_bf16 v[30:33], v[142:145], v[214:217], v[30:33]
	v_mfma_f32_16x16x32_bf16 v[26:29], v[156:159], v[214:217], v[26:29]
	v_mfma_f32_16x16x32_bf16 v[14:17], v[142:145], v[222:225], v[14:17]
	v_mfma_f32_16x16x32_bf16 v[10:13], v[156:159], v[222:225], v[10:13]
	v_mfma_f32_16x16x32_bf16 v[62:65], v[146:149], v[202:205], v[62:65]
	v_mfma_f32_16x16x32_bf16 v[58:61], v[160:163], v[202:205], v[58:61]
	v_mfma_f32_16x16x32_bf16 v[46:49], v[146:149], v[210:213], v[46:49]
	v_mfma_f32_16x16x32_bf16 v[42:45], v[160:163], v[210:213], v[42:45]
	v_mfma_f32_16x16x32_bf16 v[30:33], v[146:149], v[218:221], v[30:33]
	v_mfma_f32_16x16x32_bf16 v[26:29], v[160:163], v[218:221], v[26:29]
	v_mfma_f32_16x16x32_bf16 v[14:17], v[146:149], v[226:229], v[14:17]
	v_mfma_f32_16x16x32_bf16 v[10:13], v[160:163], v[226:229], v[10:13]
	v_mfma_f32_16x16x32_bf16 v[54:57], v[176:179], v[198:201], v[54:57]
	v_mfma_f32_16x16x32_bf16 v[50:53], v[190:193], v[198:201], v[50:53]
	v_mfma_f32_16x16x32_bf16 v[38:41], v[176:179], v[206:209], v[38:41]
	v_mfma_f32_16x16x32_bf16 v[34:37], v[190:193], v[206:209], v[34:37]
	v_mfma_f32_16x16x32_bf16 v[22:25], v[176:179], v[214:217], v[22:25]
	v_mfma_f32_16x16x32_bf16 v[18:21], v[190:193], v[214:217], v[18:21]
	v_mfma_f32_16x16x32_bf16 v[6:9], v[176:179], v[222:225], v[6:9]
	v_mfma_f32_16x16x32_bf16 v[2:5], v[190:193], v[222:225], v[2:5]
	v_mfma_f32_16x16x32_bf16 v[54:57], v[180:183], v[202:205], v[54:57]
	v_mfma_f32_16x16x32_bf16 v[50:53], v[194:197], v[202:205], v[50:53]
	v_mfma_f32_16x16x32_bf16 v[38:41], v[180:183], v[210:213], v[38:41]
	v_mfma_f32_16x16x32_bf16 v[34:37], v[194:197], v[210:213], v[34:37]
	v_mfma_f32_16x16x32_bf16 v[22:25], v[180:183], v[218:221], v[22:25]
	v_mfma_f32_16x16x32_bf16 v[18:21], v[194:197], v[218:221], v[18:21]
	v_mfma_f32_16x16x32_bf16 v[6:9], v[180:183], v[226:229], v[6:9]
	v_mfma_f32_16x16x32_bf16 v[2:5], v[194:197], v[226:229], v[2:5]
	s_setprio 0
	s_barrier
	s_add_i32 s54, 0, 0x18000
	v_add_u32_e32 v0, s54, v153
	s_add_i32 s55, 0, 0x1c000
	ds_read_b128 v[142:145], v0
	ds_read_b128 v[146:149], v0 offset:1024
	ds_read_b128 v[156:159], v0 offset:2048
	ds_read_b128 v[160:163], v0 offset:3072
	v_add_u32_e32 v0, s55, v153
	ds_read_b128 v[176:179], v0
	ds_read_b128 v[180:183], v0 offset:1024
	ds_read_b128 v[190:193], v0 offset:2048
	ds_read_b128 v[194:197], v0 offset:3072
	s_add_u32 s40, s40, 0x40000
	s_addc_u32 s41, s41, 0
	s_mov_b32 m0, s46
	ds_read_b128 v[198:201], v155 offset:32768
	ds_read_b128 v[202:205], v155 offset:33792
	ds_read_b128 v[206:209], v155 offset:34816
	ds_read_b128 v[210:213], v155 offset:35840
	ds_read_b128 v[214:217], v155 offset:36864
	ds_read_b128 v[218:221], v155 offset:37888
	ds_read_b128 v[222:225], v155 offset:38912
	ds_read_b128 v[226:229], v155 offset:39936
	global_load_lds_dwordx4 v130, s[40:41]
	v_lshl_add_u64 v[240:241], s[40:41], 0, v[134:135]
	s_mov_b32 m0, s47
	s_nop 0
	global_load_lds_dwordx4 v[240:241], off
	s_waitcnt vmcnt(8)
	s_waitcnt lgkmcnt(0)
	s_barrier
	s_setprio 1
	v_mfma_f32_16x16x32_bf16 v[126:129], v[142:145], v[198:201], v[126:129]
	v_mfma_f32_16x16x32_bf16 v[122:125], v[156:159], v[198:201], v[122:125]
	v_mfma_f32_16x16x32_bf16 v[110:113], v[142:145], v[206:209], v[110:113]
	v_mfma_f32_16x16x32_bf16 v[106:109], v[156:159], v[206:209], v[106:109]
	v_mfma_f32_16x16x32_bf16 v[94:97], v[142:145], v[214:217], v[94:97]
	v_mfma_f32_16x16x32_bf16 v[90:93], v[156:159], v[214:217], v[90:93]
	v_mfma_f32_16x16x32_bf16 v[78:81], v[142:145], v[222:225], v[78:81]
	v_mfma_f32_16x16x32_bf16 v[74:77], v[156:159], v[222:225], v[74:77]
	v_mfma_f32_16x16x32_bf16 v[126:129], v[146:149], v[202:205], v[126:129]
	v_mfma_f32_16x16x32_bf16 v[122:125], v[160:163], v[202:205], v[122:125]
	v_mfma_f32_16x16x32_bf16 v[110:113], v[146:149], v[210:213], v[110:113]
	v_mfma_f32_16x16x32_bf16 v[106:109], v[160:163], v[210:213], v[106:109]
	v_mfma_f32_16x16x32_bf16 v[94:97], v[146:149], v[218:221], v[94:97]
	v_mfma_f32_16x16x32_bf16 v[90:93], v[160:163], v[218:221], v[90:93]
	v_mfma_f32_16x16x32_bf16 v[78:81], v[146:149], v[226:229], v[78:81]
	v_mfma_f32_16x16x32_bf16 v[74:77], v[160:163], v[226:229], v[74:77]
	v_mfma_f32_16x16x32_bf16 v[118:121], v[176:179], v[198:201], v[118:121]
	v_mfma_f32_16x16x32_bf16 v[114:117], v[190:193], v[198:201], v[114:117]
	v_mfma_f32_16x16x32_bf16 v[102:105], v[176:179], v[206:209], v[102:105]
	v_mfma_f32_16x16x32_bf16 v[98:101], v[190:193], v[206:209], v[98:101]
	v_mfma_f32_16x16x32_bf16 v[86:89], v[176:179], v[214:217], v[86:89]
	v_mfma_f32_16x16x32_bf16 v[82:85], v[190:193], v[214:217], v[82:85]
	v_mfma_f32_16x16x32_bf16 v[70:73], v[176:179], v[222:225], v[70:73]
	v_mfma_f32_16x16x32_bf16 v[66:69], v[190:193], v[222:225], v[66:69]
	v_mfma_f32_16x16x32_bf16 v[118:121], v[180:183], v[202:205], v[118:121]
	v_mfma_f32_16x16x32_bf16 v[114:117], v[194:197], v[202:205], v[114:117]
	v_mfma_f32_16x16x32_bf16 v[102:105], v[180:183], v[210:213], v[102:105]
	v_mfma_f32_16x16x32_bf16 v[98:101], v[194:197], v[210:213], v[98:101]
	v_mfma_f32_16x16x32_bf16 v[86:89], v[180:183], v[218:221], v[86:89]
	v_mfma_f32_16x16x32_bf16 v[82:85], v[194:197], v[218:221], v[82:85]
	v_mfma_f32_16x16x32_bf16 v[70:73], v[180:183], v[226:229], v[70:73]
	v_mfma_f32_16x16x32_bf16 v[66:69], v[194:197], v[226:229], v[66:69]
	s_setprio 0
	s_barrier
; #define PG8_STAGE(bufoff, gbase, voff) do { _Pragma("unroll") for (int _i = 0; _i < 2; ++_i) \
;         __builtin_amdgcn_global_load_lds((const unsigned*)((const char*)(gbase) + (voff)[_i]), (LAS unsigned*)(lds + (bufoff) + ldsw + _i * 8192), 16, 0, 0); } while (0)
; #define PG8_LDA(dst, b, h) do { _Pragma("unroll") for (int m = 0; m < 4; ++m) _Pragma("unroll") for (int k = 0; k < 2; ++k) dst[m][k] = *(const LAS bf16x8*)(lds + PG8_SA(b, h) + aoff + m * 2048 + k * 1024); } while (0)
; #define PG8_MMA(ai, bj, At, Bt) do { __builtin_amdgcn_s_setprio(1); _Pragma("unroll") for (int m = 0; m < 4; ++m) _Pragma("unroll") for (int n = 0; n < 2; ++n) _Pragma("unroll") for (int k = 0; k < 2; ++k) \
;         acc[ai][bj][m][n] = __builtin_amdgcn_mfma_f32_16x16x32_bf16(Bt[n][k], At[m][k], acc[ai][bj][m][n], 0, 0, 0); __builtin_amdgcn_s_setprio(0); } while (0)
; #define PG8_WAIT_V(n) asm volatile("s_waitcnt vmcnt(" #n ")" ::: "memory")
; #define PG8_WAIT_L(n) asm volatile("s_waitcnt lgkmcnt(" #n ")" ::: "memory")
; #define PG8_BAR __builtin_amdgcn_s_barrier()
; #define PG8_SCHED __builtin_amdgcn_sched_barrier(0)
; template <class Epi>
; DI void gemm_phase(int wid0, LAS unsigned char* lds, const Gemm g, const StaticOrder& S, const Epi& E) {
;     ...
;             PG8_LDA(At, 1, 1); PG8_STAGE(PG8_SB(1, 0), b3, voffB); PG8_STAGE(PG8_SB(1, 1), b3 + hstep, voffB); PG8_STAGE(PG8_SA(1, 0), a3, voffA);
;             PG8_WAIT_V(8); PG8_WAIT_L(0); PG8_BAR; PG8_MMA(1, 0, At, B0); PG8_MMA(1, 1, At, B1); PG8_BAR; PG8_SCHED;
;         }
;         if (wr == 0) PG8_BAR;
	s_add_i32 s40, s54, s2
	v_lshl_add_u64 v[150:151], v[150:151], 0, s[30:31]
	s_mov_b32 m0, s40
	ds_read_b128 v[198:201], v155 offset:49152
	ds_read_b128 v[202:205], v155 offset:50176
	ds_read_b128 v[206:209], v155 offset:51200
	ds_read_b128 v[210:213], v155 offset:52224
	ds_read_b128 v[214:217], v155 offset:53248
	ds_read_b128 v[218:221], v155 offset:54272
	ds_read_b128 v[222:225], v155 offset:55296
	ds_read_b128 v[226:229], v155 offset:56320
	global_load_lds_dwordx4 v[150:151], off
	s_add_i32 m0, s40, 0x2000
	s_add_u32 s38, s38, 0x40080
	v_lshl_add_u64 v[150:151], v[230:231], 0, s[30:31]
	s_addc_u32 s39, s39, 0
	s_add_i32 s40, s55, s2
	global_load_lds_dwordx4 v[150:151], off
	s_mov_b32 m0, s40
	s_nop 0
	global_load_lds_dwordx4 v132, s[38:39]
	s_add_i32 m0, s40, 0x2000
	s_nop 0
	global_load_lds_dwordx4 v136, s[38:39]
	v_lshl_add_u64 v[150:151], v[236:237], 0, s[30:31]
	s_mov_b32 m0, s48
	s_nop 0
	global_load_lds_dwordx4 v[150:151], off
	v_lshl_add_u64 v[150:151], v[238:239], 0, s[30:31]
	s_mov_b32 m0, s49
	s_nop 0
	global_load_lds_dwordx4 v[150:151], off
	s_waitcnt vmcnt(8)
	s_waitcnt lgkmcnt(0)
	s_barrier
	s_setprio 1
	v_mfma_f32_16x16x32_bf16 v[62:65], v[142:145], v[198:201], v[62:65]
	v_mfma_f32_16x16x32_bf16 v[58:61], v[156:159], v[198:201], v[58:61]
	v_mfma_f32_16x16x32_bf16 v[46:49], v[142:145], v[206:209], v[46:49]
	v_mfma_f32_16x16x32_bf16 v[42:45], v[156:159], v[206:209], v[42:45]
	v_mfma_f32_16x16x32_bf16 v[30:33], v[142:145], v[214:217], v[30:33]
	v_mfma_f32_16x16x32_bf16 v[26:29], v[156:159], v[214:217], v[26:29]
	v_mfma_f32_16x16x32_bf16 v[14:17], v[142:145], v[222:225], v[14:17]
	v_mfma_f32_16x16x32_bf16 v[10:13], v[156:159], v[222:225], v[10:13]
	v_mfma_f32_16x16x32_bf16 v[62:65], v[146:149], v[202:205], v[62:65]
	v_mfma_f32_16x16x32_bf16 v[58:61], v[160:163], v[202:205], v[58:61]
	v_mfma_f32_16x16x32_bf16 v[46:49], v[146:149], v[210:213], v[46:49]
	v_mfma_f32_16x16x32_bf16 v[42:45], v[160:163], v[210:213], v[42:45]
	v_mfma_f32_16x16x32_bf16 v[30:33], v[146:149], v[218:221], v[30:33]
	v_mfma_f32_16x16x32_bf16 v[26:29], v[160:163], v[218:221], v[26:29]
	v_mfma_f32_16x16x32_bf16 v[14:17], v[146:149], v[226:229], v[14:17]
	v_mfma_f32_16x16x32_bf16 v[10:13], v[160:163], v[226:229], v[10:13]
	v_mfma_f32_16x16x32_bf16 v[54:57], v[176:179], v[198:201], v[54:57]
	v_mfma_f32_16x16x32_bf16 v[50:53], v[190:193], v[198:201], v[50:53]
	v_mfma_f32_16x16x32_bf16 v[38:41], v[176:179], v[206:209], v[38:41]
	v_mfma_f32_16x16x32_bf16 v[34:37], v[190:193], v[206:209], v[34:37]
	v_mfma_f32_16x16x32_bf16 v[22:25], v[176:179], v[214:217], v[22:25]
	v_mfma_f32_16x16x32_bf16 v[18:21], v[190:193], v[214:217], v[18:21]
	v_mfma_f32_16x16x32_bf16 v[6:9], v[176:179], v[222:225], v[6:9]
	v_mfma_f32_16x16x32_bf16 v[2:5], v[190:193], v[222:225], v[2:5]
	v_mfma_f32_16x16x32_bf16 v[54:57], v[180:183], v[202:205], v[54:57]
	v_mfma_f32_16x16x32_bf16 v[50:53], v[194:197], v[202:205], v[50:53]
	v_mfma_f32_16x16x32_bf16 v[38:41], v[180:183], v[210:213], v[38:41]
	v_mfma_f32_16x16x32_bf16 v[34:37], v[194:197], v[210:213], v[34:37]
	v_mfma_f32_16x16x32_bf16 v[22:25], v[180:183], v[218:221], v[22:25]
	v_mfma_f32_16x16x32_bf16 v[18:21], v[194:197], v[218:221], v[18:21]
	v_mfma_f32_16x16x32_bf16 v[6:9], v[180:183], v[226:229], v[6:9]
	v_mfma_f32_16x16x32_bf16 v[2:5], v[194:197], v[226:229], v[2:5]
	s_setprio 0
	s_barrier
	s_add_i32 s51, s51, 2
	s_add_u32 s28, s28, 0x100
	s_addc_u32 s29, s29, 0
	s_add_u32 s17, s17, 0x100
	s_addc_u32 s19, s19, 0
	s_cmp_gt_u32 s51, 13
	s_cbranch_scc0 .LBB0_277
	s_and_b64 vcc, exec, s[14:15]
	s_cbranch_vccz .LBB0_280
	s_barrier
